# EpiFFN regenerated pair blocks: packed f32 math, boundary taps as bounded DPP shifts (no select), four pair blocks interleaved
# baseline (speedup 1.0000x reference)
.LBB0_1404:
	s_add_u32 s16, s10, 0xfffc0080
	s_addc_u32 s17, s11, -1
	s_add_i32 s41, 0, 0x10000
	v_add_u32_e32 v132, s41, v198
	ds_read_b128 v[116:119], v132
	ds_read_b128 v[124:127], v132 offset:1024
	ds_read_b128 v[128:131], v132 offset:2048
	ds_read_b128 v[132:135], v132 offset:3072
	s_cmp_eq_u32 s40, 12
	s_cselect_b32 s35, s6, s17
	s_cselect_b32 s34, s31, s16
	s_cselect_b32 s17, s5, s39
	s_cselect_b32 s16, s36, s37
	v_lshl_add_u64 v[186:187], s[10:11], 0, v[176:177]
	s_add_i32 m0, s33, 0xc000
	ds_read_b128 v[136:139], v199
	ds_read_b128 v[140:143], v199 offset:1024
	ds_read_b128 v[144:147], v199 offset:2048
	ds_read_b128 v[148:151], v199 offset:3072
	ds_read_b128 v[152:155], v199 offset:4096
	ds_read_b128 v[178:181], v199 offset:5120
	ds_read_b128 v[182:185], v199 offset:6144
	ds_read_b128 v[200:203], v199 offset:7168
	global_load_lds_dwordx4 v[186:187], off
	v_lshl_add_u64 v[186:187], s[10:11], 0, v[174:175]
	s_add_i32 m0, s33, 0xe000
	s_nop 0
	global_load_lds_dwordx4 v[186:187], off
	s_waitcnt lgkmcnt(8)
	s_barrier
	s_waitcnt lgkmcnt(0)
	s_setprio 1
	s_waitcnt lgkmcnt(0)
	v_mfma_f32_16x16x32_bf16 v[160:163], v[116:119], v[136:139], v[160:163]
	v_mfma_f32_16x16x32_bf16 v[60:63], v[128:131], v[136:139], v[60:63]
	v_mfma_f32_16x16x32_bf16 v[120:123], v[116:119], v[144:147], v[120:123]
	v_mfma_f32_16x16x32_bf16 v[52:55], v[128:131], v[144:147], v[52:55]
	v_mfma_f32_16x16x32_bf16 v[108:111], v[116:119], v[152:155], v[108:111]
	v_mfma_f32_16x16x32_bf16 v[44:47], v[128:131], v[152:155], v[44:47]
	v_mfma_f32_16x16x32_bf16 v[100:103], v[116:119], v[182:185], v[100:103]
	v_mfma_f32_16x16x32_bf16 v[36:39], v[128:131], v[182:185], v[36:39]
	v_mfma_f32_16x16x32_bf16 v[160:163], v[124:127], v[140:143], v[160:163]
	v_mfma_f32_16x16x32_bf16 v[60:63], v[132:135], v[140:143], v[60:63]
	v_mfma_f32_16x16x32_bf16 v[120:123], v[124:127], v[148:151], v[120:123]
	v_mfma_f32_16x16x32_bf16 v[52:55], v[132:135], v[148:151], v[52:55]
	v_mfma_f32_16x16x32_bf16 v[108:111], v[124:127], v[178:181], v[108:111]
	v_mfma_f32_16x16x32_bf16 v[44:47], v[132:135], v[178:181], v[44:47]
	v_mfma_f32_16x16x32_bf16 v[100:103], v[124:127], v[200:203], v[100:103]
	v_mfma_f32_16x16x32_bf16 v[36:39], v[132:135], v[200:203], v[36:39]
	s_setprio 0
	s_barrier
	s_add_i32 s48, 0, 0x14000
	s_add_i32 s41, s41, s27
	v_add_u32_e32 v164, s48, v198
	v_lshl_add_u64 v[186:187], s[16:17], 0, v[172:173]
	s_mov_b32 m0, s41
	ds_read_b128 v[204:207], v164
	ds_read_b128 v[208:211], v164 offset:1024
	ds_read_b128 v[212:215], v164 offset:2048
	ds_read_b128 v[216:219], v164 offset:3072
	global_load_lds_dwordx4 v[186:187], off
	v_lshl_add_u64 v[186:187], s[16:17], 0, v[168:169]
	s_add_i32 m0, s41, 0x2000
	s_nop 0
	global_load_lds_dwordx4 v[186:187], off
	s_barrier
	s_waitcnt lgkmcnt(0)
	s_setprio 1
	s_waitcnt lgkmcnt(0)
	v_mfma_f32_16x16x32_bf16 v[156:159], v[204:207], v[136:139], v[156:159]
	v_mfma_f32_16x16x32_bf16 v[56:59], v[212:215], v[136:139], v[56:59]
	v_mfma_f32_16x16x32_bf16 v[112:115], v[204:207], v[144:147], v[112:115]
	v_mfma_f32_16x16x32_bf16 v[48:51], v[212:215], v[144:147], v[48:51]
	v_mfma_f32_16x16x32_bf16 v[104:107], v[204:207], v[152:155], v[104:107]
	v_mfma_f32_16x16x32_bf16 v[40:43], v[212:215], v[152:155], v[40:43]
	v_mfma_f32_16x16x32_bf16 v[96:99], v[204:207], v[182:185], v[96:99]
	v_mfma_f32_16x16x32_bf16 v[32:35], v[212:215], v[182:185], v[32:35]
	v_mfma_f32_16x16x32_bf16 v[156:159], v[208:211], v[140:143], v[156:159]
	v_mfma_f32_16x16x32_bf16 v[56:59], v[216:219], v[140:143], v[56:59]
	v_mfma_f32_16x16x32_bf16 v[112:115], v[208:211], v[148:151], v[112:115]
	v_mfma_f32_16x16x32_bf16 v[48:51], v[216:219], v[148:151], v[48:51]
	v_mfma_f32_16x16x32_bf16 v[104:107], v[208:211], v[178:181], v[104:107]
	v_mfma_f32_16x16x32_bf16 v[40:43], v[216:219], v[178:181], v[40:43]
	v_mfma_f32_16x16x32_bf16 v[96:99], v[208:211], v[200:203], v[96:99]
	v_mfma_f32_16x16x32_bf16 v[32:35], v[216:219], v[200:203], v[32:35]
	s_setprio 0
	s_mov_b32 m0, s33
	v_lshl_add_u64 v[186:187], s[34:35], 0, v[170:171]
	s_barrier
	ds_read_b128 v[136:139], v199 offset:16384
	ds_read_b128 v[140:143], v199 offset:17408
	ds_read_b128 v[144:147], v199 offset:18432
	ds_read_b128 v[148:151], v199 offset:19456
	ds_read_b128 v[152:155], v199 offset:20480
	ds_read_b128 v[178:181], v199 offset:21504
	ds_read_b128 v[182:185], v199 offset:22528
	ds_read_b128 v[200:203], v199 offset:23552
	global_load_lds_dwordx4 v[186:187], off
	v_lshl_add_u64 v[220:221], s[34:35], 0, v[166:167]
	s_mov_b32 m0, s2
	s_nop 0
	global_load_lds_dwordx4 v[220:221], off
	s_barrier
	s_waitcnt lgkmcnt(0)
	s_setprio 1
	s_waitcnt lgkmcnt(0)
	v_mfma_f32_16x16x32_bf16 v[92:95], v[116:119], v[136:139], v[92:95]
	v_mfma_f32_16x16x32_bf16 v[28:31], v[128:131], v[136:139], v[28:31]
	v_mfma_f32_16x16x32_bf16 v[84:87], v[116:119], v[144:147], v[84:87]
	v_mfma_f32_16x16x32_bf16 v[20:23], v[128:131], v[144:147], v[20:23]
	v_mfma_f32_16x16x32_bf16 v[76:79], v[116:119], v[152:155], v[76:79]
	v_mfma_f32_16x16x32_bf16 v[12:15], v[128:131], v[152:155], v[12:15]
	v_mfma_f32_16x16x32_bf16 v[68:71], v[116:119], v[182:185], v[68:71]
	v_mfma_f32_16x16x32_bf16 v[4:7], v[128:131], v[182:185], v[4:7]
	v_mfma_f32_16x16x32_bf16 v[92:95], v[124:127], v[140:143], v[92:95]
	v_mfma_f32_16x16x32_bf16 v[28:31], v[132:135], v[140:143], v[28:31]
	v_mfma_f32_16x16x32_bf16 v[84:87], v[124:127], v[148:151], v[84:87]
	v_mfma_f32_16x16x32_bf16 v[20:23], v[132:135], v[148:151], v[20:23]
	v_mfma_f32_16x16x32_bf16 v[76:79], v[124:127], v[178:181], v[76:79]
	v_mfma_f32_16x16x32_bf16 v[12:15], v[132:135], v[178:181], v[12:15]
	v_mfma_f32_16x16x32_bf16 v[68:71], v[124:127], v[200:203], v[68:71]
	v_mfma_f32_16x16x32_bf16 v[4:7], v[132:135], v[200:203], v[4:7]
	s_setprio 0
	s_barrier
	s_add_u32 s52, s16, 0x4000
	s_addc_u32 s53, s17, 0
	s_add_i32 s41, s48, s27
	v_lshl_add_u64 v[116:117], s[52:53], 0, v[172:173]
	s_mov_b32 m0, s41
	s_nop 0
	global_load_lds_dwordx4 v[116:117], off
	v_lshl_add_u64 v[116:117], s[52:53], 0, v[168:169]
	s_add_i32 m0, s41, 0x2000
	s_nop 0
	global_load_lds_dwordx4 v[116:117], off
	s_waitcnt vmcnt(6)
	s_barrier
	s_setprio 1
	v_mfma_f32_16x16x32_bf16 v[88:91], v[204:207], v[136:139], v[88:91]
	v_mfma_f32_16x16x32_bf16 v[24:27], v[212:215], v[136:139], v[24:27]
	v_mfma_f32_16x16x32_bf16 v[80:83], v[204:207], v[144:147], v[80:83]
	v_mfma_f32_16x16x32_bf16 v[16:19], v[212:215], v[144:147], v[16:19]
	v_mfma_f32_16x16x32_bf16 v[72:75], v[204:207], v[152:155], v[72:75]
	v_mfma_f32_16x16x32_bf16 v[8:11], v[212:215], v[152:155], v[8:11]
	v_mfma_f32_16x16x32_bf16 v[64:67], v[204:207], v[182:185], v[64:67]
	v_mfma_f32_16x16x32_bf16 v[0:3], v[212:215], v[182:185], v[0:3]
	v_mfma_f32_16x16x32_bf16 v[88:91], v[208:211], v[140:143], v[88:91]
	v_mfma_f32_16x16x32_bf16 v[24:27], v[216:219], v[140:143], v[24:27]
	v_mfma_f32_16x16x32_bf16 v[80:83], v[208:211], v[148:151], v[80:83]
	v_mfma_f32_16x16x32_bf16 v[16:19], v[216:219], v[148:151], v[16:19]
	v_mfma_f32_16x16x32_bf16 v[72:75], v[208:211], v[178:181], v[72:75]
	v_mfma_f32_16x16x32_bf16 v[8:11], v[216:219], v[178:181], v[8:11]
	v_mfma_f32_16x16x32_bf16 v[64:67], v[208:211], v[200:203], v[64:67]
	v_mfma_f32_16x16x32_bf16 v[0:3], v[216:219], v[200:203], v[0:3]
	s_setprio 0
	s_add_i32 s41, 0, 0x18000
	v_add_u32_e32 v132, s41, v198
	s_barrier
	ds_read_b128 v[116:119], v132
	ds_read_b128 v[124:127], v132 offset:1024
	ds_read_b128 v[128:131], v132 offset:2048
	ds_read_b128 v[132:135], v132 offset:3072
	s_add_u32 s34, s34, 0x40000
	s_addc_u32 s35, s35, 0
	s_mov_b32 m0, s78
	v_lshl_add_u64 v[204:205], s[34:35], 0, v[170:171]
	ds_read_b128 v[136:139], v199 offset:32768
	ds_read_b128 v[140:143], v199 offset:33792
	ds_read_b128 v[144:147], v199 offset:34816
	ds_read_b128 v[148:151], v199 offset:35840
	ds_read_b128 v[152:155], v199 offset:36864
	ds_read_b128 v[178:181], v199 offset:37888
	ds_read_b128 v[182:185], v199 offset:38912
	ds_read_b128 v[200:203], v199 offset:39936
	global_load_lds_dwordx4 v[204:205], off
	v_lshl_add_u64 v[204:205], s[34:35], 0, v[166:167]
	s_mov_b32 m0, s79
	s_nop 0
	global_load_lds_dwordx4 v[204:205], off
	s_waitcnt lgkmcnt(8)
	s_barrier
	s_waitcnt lgkmcnt(0)
	s_setprio 1
	s_waitcnt lgkmcnt(0)
	v_mfma_f32_16x16x32_bf16 v[160:163], v[116:119], v[136:139], v[160:163]
	v_mfma_f32_16x16x32_bf16 v[60:63], v[128:131], v[136:139], v[60:63]
	v_mfma_f32_16x16x32_bf16 v[120:123], v[116:119], v[144:147], v[120:123]
	v_mfma_f32_16x16x32_bf16 v[52:55], v[128:131], v[144:147], v[52:55]
	v_mfma_f32_16x16x32_bf16 v[108:111], v[116:119], v[152:155], v[108:111]
	v_mfma_f32_16x16x32_bf16 v[44:47], v[128:131], v[152:155], v[44:47]
	v_mfma_f32_16x16x32_bf16 v[100:103], v[116:119], v[182:185], v[100:103]
	v_mfma_f32_16x16x32_bf16 v[36:39], v[128:131], v[182:185], v[36:39]
	v_mfma_f32_16x16x32_bf16 v[160:163], v[124:127], v[140:143], v[160:163]
	v_mfma_f32_16x16x32_bf16 v[60:63], v[132:135], v[140:143], v[60:63]
	v_mfma_f32_16x16x32_bf16 v[120:123], v[124:127], v[148:151], v[120:123]
	v_mfma_f32_16x16x32_bf16 v[52:55], v[132:135], v[148:151], v[52:55]
	v_mfma_f32_16x16x32_bf16 v[108:111], v[124:127], v[178:181], v[108:111]
	v_mfma_f32_16x16x32_bf16 v[44:47], v[132:135], v[178:181], v[44:47]
	v_mfma_f32_16x16x32_bf16 v[100:103], v[124:127], v[200:203], v[100:103]
	v_mfma_f32_16x16x32_bf16 v[36:39], v[132:135], v[200:203], v[36:39]
	s_setprio 0
	s_barrier
	s_add_i32 s48, 0, 0x1c000
	s_add_u32 s34, s16, 0x8000
	s_addc_u32 s35, s17, 0
	s_add_i32 s41, s41, s27
	v_add_u32_e32 v164, s48, v198
	v_lshl_add_u64 v[222:223], s[34:35], 0, v[172:173]
	s_mov_b32 m0, s41
	ds_read_b128 v[204:207], v164
	ds_read_b128 v[208:211], v164 offset:1024
	ds_read_b128 v[212:215], v164 offset:2048
	ds_read_b128 v[216:219], v164 offset:3072
	global_load_lds_dwordx4 v[222:223], off
	v_lshl_add_u64 v[222:223], s[34:35], 0, v[168:169]
	s_add_i32 m0, s41, 0x2000
	s_nop 0
	global_load_lds_dwordx4 v[222:223], off
	s_barrier
	s_waitcnt lgkmcnt(0)
	s_setprio 1
	s_waitcnt lgkmcnt(0)
	v_mfma_f32_16x16x32_bf16 v[156:159], v[204:207], v[136:139], v[156:159]
	v_mfma_f32_16x16x32_bf16 v[56:59], v[212:215], v[136:139], v[56:59]
	v_mfma_f32_16x16x32_bf16 v[112:115], v[204:207], v[144:147], v[112:115]
	v_mfma_f32_16x16x32_bf16 v[48:51], v[212:215], v[144:147], v[48:51]
	v_mfma_f32_16x16x32_bf16 v[104:107], v[204:207], v[152:155], v[104:107]
	v_mfma_f32_16x16x32_bf16 v[40:43], v[212:215], v[152:155], v[40:43]
	v_mfma_f32_16x16x32_bf16 v[96:99], v[204:207], v[182:185], v[96:99]
	v_mfma_f32_16x16x32_bf16 v[32:35], v[212:215], v[182:185], v[32:35]
	v_mfma_f32_16x16x32_bf16 v[156:159], v[208:211], v[140:143], v[156:159]
	v_mfma_f32_16x16x32_bf16 v[56:59], v[216:219], v[140:143], v[56:59]
	v_mfma_f32_16x16x32_bf16 v[112:115], v[208:211], v[148:151], v[112:115]
	v_mfma_f32_16x16x32_bf16 v[48:51], v[216:219], v[148:151], v[48:51]
	v_mfma_f32_16x16x32_bf16 v[104:107], v[208:211], v[178:181], v[104:107]
	v_mfma_f32_16x16x32_bf16 v[40:43], v[216:219], v[178:181], v[40:43]
	v_mfma_f32_16x16x32_bf16 v[96:99], v[208:211], v[200:203], v[96:99]
	v_mfma_f32_16x16x32_bf16 v[32:35], v[216:219], v[200:203], v[32:35]
	s_setprio 0
	s_mov_b32 m0, s82
	v_lshl_add_u64 v[186:187], v[186:187], 0, s[18:19]
	s_barrier
	ds_read_b128 v[136:139], v199 offset:49152
	ds_read_b128 v[140:143], v199 offset:50176
	ds_read_b128 v[144:147], v199 offset:51200
	ds_read_b128 v[148:151], v199 offset:52224
	ds_read_b128 v[152:155], v199 offset:53248
	ds_read_b128 v[178:181], v199 offset:54272
	ds_read_b128 v[182:185], v199 offset:55296
	ds_read_b128 v[200:203], v199 offset:56320
	global_load_lds_dwordx4 v[186:187], off
	v_lshl_add_u64 v[186:187], v[220:221], 0, s[18:19]
	s_mov_b32 m0, s83
	s_nop 0
	global_load_lds_dwordx4 v[186:187], off
	s_barrier
	s_waitcnt lgkmcnt(0)
	s_setprio 1
	s_waitcnt lgkmcnt(0)
	v_mfma_f32_16x16x32_bf16 v[92:95], v[116:119], v[136:139], v[92:95]
	v_mfma_f32_16x16x32_bf16 v[28:31], v[128:131], v[136:139], v[28:31]
	v_mfma_f32_16x16x32_bf16 v[84:87], v[116:119], v[144:147], v[84:87]
	v_mfma_f32_16x16x32_bf16 v[20:23], v[128:131], v[144:147], v[20:23]
	v_mfma_f32_16x16x32_bf16 v[76:79], v[116:119], v[152:155], v[76:79]
	v_mfma_f32_16x16x32_bf16 v[12:15], v[128:131], v[152:155], v[12:15]
	v_mfma_f32_16x16x32_bf16 v[68:71], v[116:119], v[182:185], v[68:71]
	v_mfma_f32_16x16x32_bf16 v[4:7], v[128:131], v[182:185], v[4:7]
	v_mfma_f32_16x16x32_bf16 v[92:95], v[124:127], v[140:143], v[92:95]
	v_mfma_f32_16x16x32_bf16 v[28:31], v[132:135], v[140:143], v[28:31]
	v_mfma_f32_16x16x32_bf16 v[84:87], v[124:127], v[148:151], v[84:87]
	v_mfma_f32_16x16x32_bf16 v[20:23], v[132:135], v[148:151], v[20:23]
	v_mfma_f32_16x16x32_bf16 v[76:79], v[124:127], v[178:181], v[76:79]
	v_mfma_f32_16x16x32_bf16 v[12:15], v[132:135], v[178:181], v[12:15]
	v_mfma_f32_16x16x32_bf16 v[68:71], v[124:127], v[200:203], v[68:71]
	v_mfma_f32_16x16x32_bf16 v[4:7], v[132:135], v[200:203], v[4:7]
	s_setprio 0
	s_barrier
	s_add_u32 s16, s16, 0xc000
	s_addc_u32 s17, s17, 0
	s_add_i32 s34, s48, s27
	v_lshl_add_u64 v[116:117], s[16:17], 0, v[172:173]
	s_mov_b32 m0, s34
	s_nop 0
	global_load_lds_dwordx4 v[116:117], off
	v_lshl_add_u64 v[116:117], s[16:17], 0, v[168:169]
	s_add_i32 m0, s34, 0x2000
	s_nop 0
	global_load_lds_dwordx4 v[116:117], off
	s_waitcnt vmcnt(6)
	s_barrier
	s_setprio 1
	v_mfma_f32_16x16x32_bf16 v[88:91], v[204:207], v[136:139], v[88:91]
	v_mfma_f32_16x16x32_bf16 v[24:27], v[212:215], v[136:139], v[24:27]
	v_mfma_f32_16x16x32_bf16 v[80:83], v[204:207], v[144:147], v[80:83]
	v_mfma_f32_16x16x32_bf16 v[16:19], v[212:215], v[144:147], v[16:19]
	v_mfma_f32_16x16x32_bf16 v[72:75], v[204:207], v[152:155], v[72:75]
	v_mfma_f32_16x16x32_bf16 v[8:11], v[212:215], v[152:155], v[8:11]
	v_mfma_f32_16x16x32_bf16 v[64:67], v[204:207], v[182:185], v[64:67]
	v_mfma_f32_16x16x32_bf16 v[0:3], v[212:215], v[182:185], v[0:3]
	v_mfma_f32_16x16x32_bf16 v[88:91], v[208:211], v[140:143], v[88:91]
	v_mfma_f32_16x16x32_bf16 v[24:27], v[216:219], v[140:143], v[24:27]
	v_mfma_f32_16x16x32_bf16 v[80:83], v[208:211], v[148:151], v[80:83]
	v_mfma_f32_16x16x32_bf16 v[16:19], v[216:219], v[148:151], v[16:19]
	v_mfma_f32_16x16x32_bf16 v[72:75], v[208:211], v[178:181], v[72:75]
	v_mfma_f32_16x16x32_bf16 v[8:11], v[216:219], v[178:181], v[8:11]
	v_mfma_f32_16x16x32_bf16 v[64:67], v[208:211], v[200:203], v[64:67]
	v_mfma_f32_16x16x32_bf16 v[0:3], v[216:219], v[200:203], v[0:3]
	s_setprio 0
	s_add_i32 s40, s40, 2
	s_add_u32 s37, s37, 0x10000
	s_addc_u32 s39, s39, 0
	s_add_u32 s10, s10, 0x100
	s_addc_u32 s11, s11, 0
	s_cmp_gt_u32 s40, 13
	s_barrier
	s_cbranch_scc0 .LBB0_1404
	v_mov_b32_e32 v116, v188
	s_lshl_b32 s6, s38, 7
	v_readfirstlane_b32 s10, v116
	s_lshr_b32 s5, s10, 1
	v_and_b32_e32 v200, 15, v116
	s_and_b32 s5, s5, 0x60
	v_lshrrev_b32_e32 v116, 1, v116
	s_or_b32 s6, s5, s6
	v_and_b32_e32 v116, 24, v116
	v_or_b32_e32 v182, s6, v116
	v_ashrrev_i32_e32 v183, 31, v182
	v_lshlrev_b64 v[118:119], 2, v[182:183]
	v_lshl_add_u64 v[184:185], s[42:43], 0, v[118:119]
	global_load_dwordx4 v[124:127], v[184:185], off
	v_lshl_add_u64 v[128:129], s[58:59], 0, v[118:119]
	global_load_dwordx4 v[128:131], v[128:129], off
	v_lshl_add_u64 v[132:133], s[60:61], 0, v[118:119]
	global_load_dwordx4 v[132:135], v[132:133], off
	v_lshl_add_u64 v[186:187], s[46:47], 0, v[118:119]
	global_load_dwordx4 v[136:139], v[186:187], off
	v_lshl_add_u64 v[140:141], s[12:13], 0, v[118:119]
	global_load_dwordx4 v[140:143], v[140:141], off
	v_lshl_add_u64 v[144:145], s[50:51], 0, v[118:119]
	global_load_dwordx4 v[144:147], v[144:145], off
	v_lshl_add_u64 v[148:149], s[20:21], 0, v[118:119]
	global_load_dwordx4 v[148:151], v[148:149], off
	v_lshl_add_u64 v[118:119], s[44:45], 0, v[118:119]
	global_load_dwordx4 v[152:155], v[118:119], off
	v_mov_b32_e32 v254, 0xbfb8aa3b
	v_mov_b32_e32 v255, 0xbfb8aa3b
	v_mov_b32_e32 v252, 1.0
	v_mov_b32_e32 v253, 1.0
	v_cmp_eq_u32_e32 vcc, 15, v200
	v_cmp_eq_u32_e64 s[34:35], 0, v200
	s_nop 0
	s_nop 0
	v_mov_b32_e32 v180, v165
	s_lshl_b32 s11, s7, 8
	s_ashr_i32 s7, s10, 2
	s_andn2_b32 s7, s7, 63
	s_add_i32 s31, s7, s11
	v_mov_b32_e32 v181, v165
	s_ashr_i32 s10, s31, 6
	s_ashr_i32 s11, s10, 31
	s_lshl_b32 s16, s38, 8
	s_lshl_b64 s[52:53], s[10:11], 2
	v_cmp_gt_u32_e64 s[36:37], 2, v200
	s_ashr_i32 s17, s16, 31
	v_or_b32_e32 v183, s52, v200
	s_waitcnt vmcnt(0)
	v_pk_fma_f32 v[208:209], v[160:161], v[128:129], v[136:137]
	v_pk_fma_f32 v[220:221], v[162:163], v[130:131], v[138:139]
	v_cndmask_b32_e64 v224, v120, v160, vcc
	v_cndmask_b32_e64 v232, v108, v120, vcc
	v_pk_fma_f32 v[210:211], v[156:157], v[144:145], v[152:153]
	v_pk_fma_f32 v[222:223], v[158:159], v[146:147], v[154:155]
	v_cndmask_b32_e64 v225, v121, v161, vcc
	v_cndmask_b32_e64 v233, v109, v121, vcc
	v_fmac_f32_dpp v208, v160, v124 row_shr:1 row_mask:0xf bank_mask:0xf bound_ctrl:1
	v_fmac_f32_dpp v220, v162, v126 row_shr:1 row_mask:0xf bank_mask:0xf bound_ctrl:1
	v_cndmask_b32_e64 v226, v112, v156, vcc
	v_cndmask_b32_e64 v234, v104, v112, vcc
	v_fmac_f32_dpp v209, v161, v125 row_shr:1 row_mask:0xf bank_mask:0xf bound_ctrl:1
	v_fmac_f32_dpp v221, v163, v127 row_shr:1 row_mask:0xf bank_mask:0xf bound_ctrl:1
	v_cndmask_b32_e64 v227, v113, v157, vcc
	v_cndmask_b32_e64 v235, v105, v113, vcc
	v_fmac_f32_dpp v210, v156, v140 row_shr:1 row_mask:0xf bank_mask:0xf bound_ctrl:1
	v_fmac_f32_dpp v222, v158, v142 row_shr:1 row_mask:0xf bank_mask:0xf bound_ctrl:1
	v_pk_fma_f32 v[228:229], v[120:121], v[128:129], v[136:137]
	v_pk_fma_f32 v[240:241], v[108:109], v[128:129], v[136:137]
	v_fmac_f32_dpp v211, v157, v141 row_shr:1 row_mask:0xf bank_mask:0xf bound_ctrl:1
	v_fmac_f32_dpp v223, v159, v143 row_shr:1 row_mask:0xf bank_mask:0xf bound_ctrl:1
	v_pk_fma_f32 v[230:231], v[112:113], v[144:145], v[152:153]
	v_pk_fma_f32 v[242:243], v[104:105], v[144:145], v[152:153]
	v_cndmask_b32_e64 v204, v160, v120, s[34:35]
	v_cndmask_b32_e64 v212, v162, v122, s[34:35]
	v_fmac_f32_dpp v228, v224, v124 row_ror:1 row_mask:0xf bank_mask:0xf bound_ctrl:1
	v_fmac_f32_dpp v240, v232, v124 row_ror:1 row_mask:0xf bank_mask:0xf bound_ctrl:1
	v_cndmask_b32_e64 v205, v161, v121, s[34:35]
	v_cndmask_b32_e64 v213, v163, v123, s[34:35]
	v_fmac_f32_dpp v229, v225, v125 row_ror:1 row_mask:0xf bank_mask:0xf bound_ctrl:1
	v_fmac_f32_dpp v241, v233, v125 row_ror:1 row_mask:0xf bank_mask:0xf bound_ctrl:1
	v_cndmask_b32_e64 v206, v156, v112, s[34:35]
	v_cndmask_b32_e64 v214, v158, v114, s[34:35]
	v_fmac_f32_dpp v230, v226, v140 row_ror:1 row_mask:0xf bank_mask:0xf bound_ctrl:1
	v_fmac_f32_dpp v242, v234, v140 row_ror:1 row_mask:0xf bank_mask:0xf bound_ctrl:1
	v_cndmask_b32_e64 v207, v157, v113, s[34:35]
	v_cndmask_b32_e64 v215, v159, v115, s[34:35]
	v_fmac_f32_dpp v231, v227, v141 row_ror:1 row_mask:0xf bank_mask:0xf bound_ctrl:1
	v_fmac_f32_dpp v243, v235, v141 row_ror:1 row_mask:0xf bank_mask:0xf bound_ctrl:1
	v_fmac_f32_dpp v208, v204, v132 row_ror:15 row_mask:0xf bank_mask:0xf
	v_fmac_f32_dpp v220, v212, v134 row_ror:15 row_mask:0xf bank_mask:0xf
	v_cndmask_b32_e64 v224, v120, v108, s[34:35]
	v_cndmask_b32_e64 v232, v108, v100, s[34:35]
	v_fmac_f32_dpp v209, v205, v133 row_ror:15 row_mask:0xf bank_mask:0xf
	v_fmac_f32_dpp v221, v213, v135 row_ror:15 row_mask:0xf bank_mask:0xf
	v_cndmask_b32_e64 v225, v121, v109, s[34:35]
	v_cndmask_b32_e64 v233, v109, v101, s[34:35]
	v_fmac_f32_dpp v210, v206, v148 row_ror:15 row_mask:0xf bank_mask:0xf
	v_fmac_f32_dpp v222, v214, v150 row_ror:15 row_mask:0xf bank_mask:0xf
	v_cndmask_b32_e64 v226, v112, v104, s[34:35]
	v_cndmask_b32_e64 v234, v104, v96, s[34:35]
	v_fmac_f32_dpp v211, v207, v149 row_ror:15 row_mask:0xf bank_mask:0xf
	v_fmac_f32_dpp v223, v215, v151 row_ror:15 row_mask:0xf bank_mask:0xf
	v_cndmask_b32_e64 v227, v113, v105, s[34:35]
	v_cndmask_b32_e64 v235, v105, v97, s[34:35]
	v_pk_mul_f32 v[204:205], v[254:255], v[208:209]
	v_pk_mul_f32 v[212:213], v[254:255], v[220:221]
	v_fmac_f32_dpp v228, v224, v132 row_ror:15 row_mask:0xf bank_mask:0xf
	v_fmac_f32_dpp v240, v232, v132 row_ror:15 row_mask:0xf bank_mask:0xf
	v_exp_f32_e32 v204, v204
	v_exp_f32_e32 v212, v212
	v_fmac_f32_dpp v229, v225, v133 row_ror:15 row_mask:0xf bank_mask:0xf
	v_fmac_f32_dpp v241, v233, v133 row_ror:15 row_mask:0xf bank_mask:0xf
	v_exp_f32_e32 v205, v205
	v_exp_f32_e32 v213, v213
	v_fmac_f32_dpp v230, v226, v148 row_ror:15 row_mask:0xf bank_mask:0xf
	v_fmac_f32_dpp v242, v234, v148 row_ror:15 row_mask:0xf bank_mask:0xf
	v_pk_add_f32 v[204:205], v[204:205], v[252:253]
	v_pk_add_f32 v[212:213], v[212:213], v[252:253]
	v_fmac_f32_dpp v231, v227, v149 row_ror:15 row_mask:0xf bank_mask:0xf
	v_fmac_f32_dpp v243, v235, v149 row_ror:15 row_mask:0xf bank_mask:0xf
	v_rcp_f32_e32 v204, v204
	v_rcp_f32_e32 v212, v212
	v_pk_mul_f32 v[224:225], v[254:255], v[228:229]
	v_pk_mul_f32 v[232:233], v[254:255], v[240:241]
	v_rcp_f32_e32 v205, v205
	v_rcp_f32_e32 v213, v213
	v_exp_f32_e32 v224, v224
	v_exp_f32_e32 v232, v232
	v_pk_mul_f32 v[208:209], v[208:209], v[204:205]
	v_pk_mul_f32 v[220:221], v[220:221], v[212:213]
	v_exp_f32_e32 v225, v225
	v_exp_f32_e32 v233, v233
	v_pk_mul_f32 v[210:211], v[210:211], v[208:209]
	v_pk_mul_f32 v[222:223], v[222:223], v[220:221]
	v_pk_add_f32 v[224:225], v[224:225], v[252:253]
	v_pk_add_f32 v[232:233], v[232:233], v[252:253]
	v_rcp_f32_e32 v224, v224
	v_rcp_f32_e32 v232, v232
	v_rcp_f32_e32 v225, v225
	v_rcp_f32_e32 v233, v233
	v_pk_mul_f32 v[228:229], v[228:229], v[224:225]
	v_pk_mul_f32 v[240:241], v[240:241], v[232:233]
	v_pk_mul_f32 v[230:231], v[230:231], v[228:229]
	v_pk_mul_f32 v[242:243], v[242:243], v[240:241]
	s_nop 1
	v_cvt_pk_bf16_f32 v118, v210, v211
	v_lshlrev_b32_e32 v178, 1, v116
	v_cvt_pk_bf16_f32 v119, v222, v223
	s_and_saveexec_b64 s[10:11], s[36:37]
	s_cbranch_execz .LBB0_1407
	v_mov_b64_e32 v[116:117], s[0:1]
	v_mad_i64_i32 v[116:117], s[38:39], v183, s66, v[116:117]
	v_lshl_add_u64 v[116:117], s[16:17], 1, v[116:117]
	s_lshl_b32 s48, s5, 1
	v_lshl_add_u64 v[116:117], v[116:117], 0, s[48:49]
	v_mov_b32_e32 v179, v165
	v_lshl_add_u64 v[116:117], v[116:117], 0, v[178:179]
	v_cvt_pk_bf16_f32 v180, v160, v161
	v_cvt_pk_bf16_f32 v181, v162, v163
	global_store_dwordx2 v[116:117], v[180:181], off
	v_cvt_pk_bf16_f32 v180, v156, v157
	v_cvt_pk_bf16_f32 v181, v158, v159
	global_store_dwordx2 v[116:117], v[180:181], off offset:256
.LBB0_1407:
	s_or_b64 exec, exec, s[10:11]
	s_nop 0
	s_nop 0
	s_nop 0
	v_cndmask_b32_e64 v244, v122, v162, vcc
	v_cndmask_b32_e64 v204, v110, v122, vcc
	v_cndmask_b32_e64 v214, v100, v108, vcc
	v_cndmask_b32_e64 v228, v102, v110, vcc
	v_cndmask_b32_e64 v245, v123, v163, vcc
	v_cndmask_b32_e64 v205, v111, v123, vcc
	v_cndmask_b32_e64 v215, v101, v109, vcc
	v_cndmask_b32_e64 v229, v103, v111, vcc
	v_cndmask_b32_e64 v246, v114, v158, vcc
	v_cndmask_b32_e64 v206, v106, v114, vcc
	v_cndmask_b32_e64 v220, v96, v104, vcc
	v_cndmask_b32_e64 v232, v98, v106, vcc
	v_cndmask_b32_e64 v247, v115, v159, vcc
	v_cndmask_b32_e64 v207, v107, v115, vcc
	v_cndmask_b32_e64 v221, v97, v105, vcc
	v_cndmask_b32_e64 v233, v99, v107, vcc
	v_pk_fma_f32 v[248:249], v[122:123], v[130:131], v[138:139]
	v_pk_fma_f32 v[208:209], v[110:111], v[130:131], v[138:139]
	v_pk_fma_f32 v[224:225], v[100:101], v[128:129], v[136:137]
	v_pk_fma_f32 v[234:235], v[102:103], v[130:131], v[138:139]
	v_pk_fma_f32 v[250:251], v[114:115], v[146:147], v[154:155]
	v_pk_fma_f32 v[212:213], v[106:107], v[146:147], v[154:155]
	v_pk_fma_f32 v[226:227], v[96:97], v[144:145], v[152:153]
	v_pk_fma_f32 v[240:241], v[98:99], v[146:147], v[154:155]
	v_fmac_f32_dpp v248, v244, v126 row_ror:1 row_mask:0xf bank_mask:0xf bound_ctrl:1
	v_fmac_f32_dpp v208, v204, v126 row_ror:1 row_mask:0xf bank_mask:0xf bound_ctrl:1
	v_fmac_f32_dpp v224, v214, v124 row_ror:1 row_mask:0xf bank_mask:0xf bound_ctrl:1
	v_fmac_f32_dpp v234, v228, v126 row_ror:1 row_mask:0xf bank_mask:0xf bound_ctrl:1
	v_fmac_f32_dpp v249, v245, v127 row_ror:1 row_mask:0xf bank_mask:0xf bound_ctrl:1
	v_fmac_f32_dpp v209, v205, v127 row_ror:1 row_mask:0xf bank_mask:0xf bound_ctrl:1
	v_fmac_f32_dpp v225, v215, v125 row_ror:1 row_mask:0xf bank_mask:0xf bound_ctrl:1
	v_fmac_f32_dpp v235, v229, v127 row_ror:1 row_mask:0xf bank_mask:0xf bound_ctrl:1
	v_fmac_f32_dpp v250, v246, v142 row_ror:1 row_mask:0xf bank_mask:0xf bound_ctrl:1
	v_fmac_f32_dpp v212, v206, v142 row_ror:1 row_mask:0xf bank_mask:0xf bound_ctrl:1
	v_fmac_f32_dpp v226, v220, v140 row_ror:1 row_mask:0xf bank_mask:0xf bound_ctrl:1
	v_fmac_f32_dpp v240, v232, v142 row_ror:1 row_mask:0xf bank_mask:0xf bound_ctrl:1
	v_fmac_f32_dpp v251, v247, v143 row_ror:1 row_mask:0xf bank_mask:0xf bound_ctrl:1
	v_fmac_f32_dpp v213, v207, v143 row_ror:1 row_mask:0xf bank_mask:0xf bound_ctrl:1
	v_fmac_f32_dpp v227, v221, v141 row_ror:1 row_mask:0xf bank_mask:0xf bound_ctrl:1
	v_fmac_f32_dpp v241, v233, v143 row_ror:1 row_mask:0xf bank_mask:0xf bound_ctrl:1
	v_cndmask_b32_e64 v244, v122, v110, s[34:35]
	v_cndmask_b32_e64 v204, v110, v102, s[34:35]
	v_fmac_f32_dpp v224, v100, v132 row_shl:1 row_mask:0xf bank_mask:0xf bound_ctrl:1
	v_fmac_f32_dpp v234, v102, v134 row_shl:1 row_mask:0xf bank_mask:0xf bound_ctrl:1
	v_cndmask_b32_e64 v245, v123, v111, s[34:35]
	v_cndmask_b32_e64 v205, v111, v103, s[34:35]
	v_fmac_f32_dpp v225, v101, v133 row_shl:1 row_mask:0xf bank_mask:0xf bound_ctrl:1
	v_fmac_f32_dpp v235, v103, v135 row_shl:1 row_mask:0xf bank_mask:0xf bound_ctrl:1
	v_cndmask_b32_e64 v246, v114, v106, s[34:35]
	v_cndmask_b32_e64 v206, v106, v98, s[34:35]
	v_fmac_f32_dpp v226, v96, v148 row_shl:1 row_mask:0xf bank_mask:0xf bound_ctrl:1
	v_fmac_f32_dpp v240, v98, v150 row_shl:1 row_mask:0xf bank_mask:0xf bound_ctrl:1
	v_cndmask_b32_e64 v247, v115, v107, s[34:35]
	v_cndmask_b32_e64 v207, v107, v99, s[34:35]
	v_fmac_f32_dpp v227, v97, v149 row_shl:1 row_mask:0xf bank_mask:0xf bound_ctrl:1
	v_fmac_f32_dpp v241, v99, v151 row_shl:1 row_mask:0xf bank_mask:0xf bound_ctrl:1
	v_fmac_f32_dpp v248, v244, v134 row_ror:15 row_mask:0xf bank_mask:0xf
	v_fmac_f32_dpp v208, v204, v134 row_ror:15 row_mask:0xf bank_mask:0xf
	v_pk_mul_f32 v[214:215], v[254:255], v[224:225]
	v_pk_mul_f32 v[228:229], v[254:255], v[234:235]
	v_fmac_f32_dpp v249, v245, v135 row_ror:15 row_mask:0xf bank_mask:0xf
	v_fmac_f32_dpp v209, v205, v135 row_ror:15 row_mask:0xf bank_mask:0xf
	v_exp_f32_e32 v214, v214
	v_exp_f32_e32 v228, v228
	v_fmac_f32_dpp v250, v246, v150 row_ror:15 row_mask:0xf bank_mask:0xf
	v_fmac_f32_dpp v212, v206, v150 row_ror:15 row_mask:0xf bank_mask:0xf
	v_exp_f32_e32 v215, v215
	v_exp_f32_e32 v229, v229
	v_fmac_f32_dpp v251, v247, v151 row_ror:15 row_mask:0xf bank_mask:0xf
	v_fmac_f32_dpp v213, v207, v151 row_ror:15 row_mask:0xf bank_mask:0xf
	v_pk_add_f32 v[214:215], v[214:215], v[252:253]
	v_pk_add_f32 v[228:229], v[228:229], v[252:253]
	v_pk_mul_f32 v[244:245], v[254:255], v[248:249]
	v_pk_mul_f32 v[204:205], v[254:255], v[208:209]
	v_rcp_f32_e32 v214, v214
	v_rcp_f32_e32 v228, v228
	v_exp_f32_e32 v244, v244
	v_exp_f32_e32 v204, v204
	v_rcp_f32_e32 v215, v215
	v_rcp_f32_e32 v229, v229
	v_exp_f32_e32 v245, v245
	v_exp_f32_e32 v205, v205
	v_pk_mul_f32 v[224:225], v[224:225], v[214:215]
	v_pk_mul_f32 v[234:235], v[234:235], v[228:229]
	v_pk_add_f32 v[244:245], v[244:245], v[252:253]
	v_pk_add_f32 v[204:205], v[204:205], v[252:253]
	v_pk_mul_f32 v[226:227], v[226:227], v[224:225]
	v_pk_mul_f32 v[240:241], v[240:241], v[234:235]
	v_rcp_f32_e32 v244, v244
	v_rcp_f32_e32 v204, v204
	v_rcp_f32_e32 v245, v245
	v_rcp_f32_e32 v205, v205
	v_pk_mul_f32 v[248:249], v[248:249], v[244:245]
	v_pk_mul_f32 v[208:209], v[208:209], v[204:205]
	v_pk_mul_f32 v[250:251], v[250:251], v[248:249]
	v_pk_mul_f32 v[212:213], v[212:213], v[208:209]
	s_nop 0
	s_nop 0
	s_nop 0
	v_cvt_pk_bf16_f32 v116, v230, v231
	v_cvt_pk_bf16_f32 v117, v250, v251
	s_nop 0
	s_nop 0
	s_nop 0
	s_nop 0
	s_nop 0
	v_cvt_pk_bf16_f32 v112, v242, v243
	v_cvt_pk_bf16_f32 v113, v212, v213
	s_nop 0
	s_nop 0
	s_nop 0
	s_nop 0
	s_nop 0
	v_cmp_lt_u32_e64 s[38:39], 13, v200
	v_add_u32_e32 v180, -12, v200
	v_cvt_pk_bf16_f32 v104, v226, v227
	v_cvt_pk_bf16_f32 v105, v240, v241
	s_and_saveexec_b64 s[10:11], s[38:39]
	s_cbranch_execz .LBB0_1409
	v_mov_b32_e32 v181, v165
	v_lshl_add_u64 v[106:107], s[52:53], 0, v[180:181]
	v_mov_b64_e32 v[108:109], s[0:1]
	s_movk_i32 s48, 0x2c00
	v_mad_u64_u32 v[108:109], s[40:41], v106, s48, v[108:109]
	v_mad_i32_i24 v109, v107, s48, v109
	v_lshl_add_u64 v[106:107], s[16:17], 1, v[108:109]
	s_lshl_b32 s48, s5, 1
	v_lshl_add_u64 v[106:107], v[106:107], 0, s[48:49]
	v_mov_b32_e32 v179, v165
	s_movk_i32 s66, 0x2c00
	v_lshl_add_u64 v[106:107], v[106:107], 0, v[178:179]
	v_cvt_pk_bf16_f32 v100, v100, v101
	v_cvt_pk_bf16_f32 v101, v102, v103
	global_store_dwordx2 v[106:107], v[100:101], off
	v_cvt_pk_bf16_f32 v96, v96, v97
	v_cvt_pk_bf16_f32 v97, v98, v99
	global_store_dwordx2 v[106:107], v[96:97], off offset:256
.LBB0_1409:
	s_or_b64 exec, exec, s[10:11]
	v_pk_fma_f32 v[244:245], v[92:93], v[128:129], v[136:137]
	v_pk_fma_f32 v[206:207], v[94:95], v[130:131], v[138:139]
	v_cndmask_b32_e64 v214, v84, v92, vcc
	v_cndmask_b32_e64 v232, v86, v94, vcc
	v_pk_fma_f32 v[246:247], v[88:89], v[144:145], v[152:153]
	v_pk_fma_f32 v[208:209], v[90:91], v[146:147], v[154:155]
	v_cndmask_b32_e64 v215, v85, v93, vcc
	v_cndmask_b32_e64 v233, v87, v95, vcc
	v_fmac_f32_dpp v244, v92, v124 row_shr:1 row_mask:0xf bank_mask:0xf bound_ctrl:1
	v_fmac_f32_dpp v206, v94, v126 row_shr:1 row_mask:0xf bank_mask:0xf bound_ctrl:1
	v_cndmask_b32_e64 v220, v80, v88, vcc
	v_cndmask_b32_e64 v234, v82, v90, vcc
	v_fmac_f32_dpp v245, v93, v125 row_shr:1 row_mask:0xf bank_mask:0xf bound_ctrl:1
	v_fmac_f32_dpp v207, v95, v127 row_shr:1 row_mask:0xf bank_mask:0xf bound_ctrl:1
	v_cndmask_b32_e64 v221, v81, v89, vcc
	v_cndmask_b32_e64 v235, v83, v91, vcc
	v_fmac_f32_dpp v246, v88, v140 row_shr:1 row_mask:0xf bank_mask:0xf bound_ctrl:1
	v_fmac_f32_dpp v208, v90, v142 row_shr:1 row_mask:0xf bank_mask:0xf bound_ctrl:1
	v_pk_fma_f32 v[224:225], v[84:85], v[128:129], v[136:137]
	v_pk_fma_f32 v[230:231], v[86:87], v[130:131], v[138:139]
	v_fmac_f32_dpp v247, v89, v141 row_shr:1 row_mask:0xf bank_mask:0xf bound_ctrl:1
	v_fmac_f32_dpp v209, v91, v143 row_shr:1 row_mask:0xf bank_mask:0xf bound_ctrl:1
	v_pk_fma_f32 v[228:229], v[80:81], v[144:145], v[152:153]
	v_pk_fma_f32 v[242:243], v[82:83], v[146:147], v[154:155]
	v_cndmask_b32_e64 v210, v92, v84, s[34:35]
	v_cndmask_b32_e64 v248, v94, v86, s[34:35]
	v_fmac_f32_dpp v224, v214, v124 row_ror:1 row_mask:0xf bank_mask:0xf bound_ctrl:1
	v_fmac_f32_dpp v230, v232, v126 row_ror:1 row_mask:0xf bank_mask:0xf bound_ctrl:1
	v_cndmask_b32_e64 v211, v93, v85, s[34:35]
	v_cndmask_b32_e64 v249, v95, v87, s[34:35]
	v_fmac_f32_dpp v225, v215, v125 row_ror:1 row_mask:0xf bank_mask:0xf bound_ctrl:1
	v_fmac_f32_dpp v231, v233, v127 row_ror:1 row_mask:0xf bank_mask:0xf bound_ctrl:1
	v_cndmask_b32_e64 v222, v88, v80, s[34:35]
	v_cndmask_b32_e64 v204, v90, v82, s[34:35]
	v_fmac_f32_dpp v228, v220, v140 row_ror:1 row_mask:0xf bank_mask:0xf bound_ctrl:1
	v_fmac_f32_dpp v242, v234, v142 row_ror:1 row_mask:0xf bank_mask:0xf bound_ctrl:1
	v_cndmask_b32_e64 v223, v89, v81, s[34:35]
	v_cndmask_b32_e64 v205, v91, v83, s[34:35]
	v_fmac_f32_dpp v229, v221, v141 row_ror:1 row_mask:0xf bank_mask:0xf bound_ctrl:1
	v_fmac_f32_dpp v243, v235, v143 row_ror:1 row_mask:0xf bank_mask:0xf bound_ctrl:1
	v_fmac_f32_dpp v244, v210, v132 row_ror:15 row_mask:0xf bank_mask:0xf
	v_fmac_f32_dpp v206, v248, v134 row_ror:15 row_mask:0xf bank_mask:0xf
	v_cndmask_b32_e64 v214, v84, v76, s[34:35]
	v_cndmask_b32_e64 v232, v86, v78, s[34:35]
	v_fmac_f32_dpp v245, v211, v133 row_ror:15 row_mask:0xf bank_mask:0xf
	v_fmac_f32_dpp v207, v249, v135 row_ror:15 row_mask:0xf bank_mask:0xf
	v_cndmask_b32_e64 v215, v85, v77, s[34:35]
	v_cndmask_b32_e64 v233, v87, v79, s[34:35]
	v_fmac_f32_dpp v246, v222, v148 row_ror:15 row_mask:0xf bank_mask:0xf
	v_fmac_f32_dpp v208, v204, v150 row_ror:15 row_mask:0xf bank_mask:0xf
	v_cndmask_b32_e64 v220, v80, v72, s[34:35]
	v_cndmask_b32_e64 v234, v82, v74, s[34:35]
	v_fmac_f32_dpp v247, v223, v149 row_ror:15 row_mask:0xf bank_mask:0xf
	v_fmac_f32_dpp v209, v205, v151 row_ror:15 row_mask:0xf bank_mask:0xf
	v_cndmask_b32_e64 v221, v81, v73, s[34:35]
	v_cndmask_b32_e64 v235, v83, v75, s[34:35]
	v_pk_mul_f32 v[210:211], v[254:255], v[244:245]
	v_pk_mul_f32 v[248:249], v[254:255], v[206:207]
	v_fmac_f32_dpp v224, v214, v132 row_ror:15 row_mask:0xf bank_mask:0xf
	v_fmac_f32_dpp v230, v232, v134 row_ror:15 row_mask:0xf bank_mask:0xf
	v_exp_f32_e32 v210, v210
	v_exp_f32_e32 v248, v248
	v_fmac_f32_dpp v225, v215, v133 row_ror:15 row_mask:0xf bank_mask:0xf
	v_fmac_f32_dpp v231, v233, v135 row_ror:15 row_mask:0xf bank_mask:0xf
	v_exp_f32_e32 v211, v211
	v_exp_f32_e32 v249, v249
	v_fmac_f32_dpp v228, v220, v148 row_ror:15 row_mask:0xf bank_mask:0xf
	v_fmac_f32_dpp v242, v234, v150 row_ror:15 row_mask:0xf bank_mask:0xf
	v_pk_add_f32 v[210:211], v[210:211], v[252:253]
	v_pk_add_f32 v[248:249], v[248:249], v[252:253]
	v_fmac_f32_dpp v229, v221, v149 row_ror:15 row_mask:0xf bank_mask:0xf
	v_fmac_f32_dpp v243, v235, v151 row_ror:15 row_mask:0xf bank_mask:0xf
	v_rcp_f32_e32 v210, v210
	v_rcp_f32_e32 v248, v248
	v_pk_mul_f32 v[214:215], v[254:255], v[224:225]
	v_pk_mul_f32 v[232:233], v[254:255], v[230:231]
	v_rcp_f32_e32 v211, v211
	v_rcp_f32_e32 v249, v249
	v_exp_f32_e32 v214, v214
	v_exp_f32_e32 v232, v232
	v_pk_mul_f32 v[244:245], v[244:245], v[210:211]
	v_pk_mul_f32 v[206:207], v[206:207], v[248:249]
	v_exp_f32_e32 v215, v215
	v_exp_f32_e32 v233, v233
	v_pk_mul_f32 v[246:247], v[246:247], v[244:245]
	v_pk_mul_f32 v[208:209], v[208:209], v[206:207]
	v_pk_add_f32 v[214:215], v[214:215], v[252:253]
	v_pk_add_f32 v[232:233], v[232:233], v[252:253]
	v_rcp_f32_e32 v214, v214
	v_rcp_f32_e32 v232, v232
	v_rcp_f32_e32 v215, v215
	v_rcp_f32_e32 v233, v233
	v_pk_mul_f32 v[224:225], v[224:225], v[214:215]
	v_pk_mul_f32 v[230:231], v[230:231], v[232:233]
	v_pk_mul_f32 v[228:229], v[228:229], v[224:225]
	v_pk_mul_f32 v[242:243], v[242:243], v[230:231]
	s_nop 0
	s_nop 0
	s_nop 0
	s_nop 0
	s_add_i32 s85, s31, 0x80
	s_ashr_i32 s10, s85, 6
	s_ashr_i32 s11, s10, 31
	s_lshl_b64 s[10:11], s[10:11], 2
	v_or_b32_e32 v156, s10, v200
	v_cvt_pk_bf16_f32 v96, v246, v247
	v_cvt_pk_bf16_f32 v97, v208, v209
	s_and_saveexec_b64 s[40:41], s[36:37]
	s_cbranch_execz .LBB0_1411
	v_mov_b64_e32 v[98:99], s[0:1]
	v_mad_i64_i32 v[98:99], s[86:87], v156, s66, v[98:99]
	v_lshl_add_u64 v[98:99], s[16:17], 1, v[98:99]
	s_lshl_b32 s48, s5, 1
	v_lshl_add_u64 v[98:99], v[98:99], 0, s[48:49]
	v_mov_b32_e32 v179, v165
	v_lshl_add_u64 v[98:99], v[98:99], 0, v[178:179]
	v_cvt_pk_bf16_f32 v100, v92, v93
	v_cvt_pk_bf16_f32 v101, v94, v95
	global_store_dwordx2 v[98:99], v[100:101], off
	v_cvt_pk_bf16_f32 v100, v88, v89
	v_cvt_pk_bf16_f32 v101, v90, v91
	global_store_dwordx2 v[98:99], v[100:101], off offset:256
.LBB0_1411:
	s_or_b64 exec, exec, s[40:41]
	s_nop 0
	s_nop 0
	s_nop 0
	s_nop 0
	s_nop 0
	s_nop 0
	v_cndmask_b32_e64 v250, v76, v84, vcc
	v_cndmask_b32_e64 v210, v78, v86, vcc
	v_cndmask_b32_e64 v204, v68, v76, vcc
	v_cndmask_b32_e64 v224, v70, v78, vcc
	v_cndmask_b32_e64 v251, v77, v85, vcc
	v_cndmask_b32_e64 v211, v79, v87, vcc
	v_cndmask_b32_e64 v205, v69, v77, vcc
	v_cndmask_b32_e64 v225, v71, v79, vcc
	v_cndmask_b32_e64 v212, v72, v80, vcc
	v_cndmask_b32_e64 v222, v74, v82, vcc
	v_cndmask_b32_e64 v206, v64, v72, vcc
	v_cndmask_b32_e64 v232, v66, v74, vcc
	v_cndmask_b32_e64 v213, v73, v81, vcc
	v_cndmask_b32_e64 v223, v75, v83, vcc
	v_cndmask_b32_e64 v207, v65, v73, vcc
	v_cndmask_b32_e64 v233, v67, v75, vcc
	v_pk_fma_f32 v[226:227], v[76:77], v[128:129], v[136:137]
	v_pk_fma_f32 v[244:245], v[78:79], v[130:131], v[138:139]
	v_pk_fma_f32 v[214:215], v[68:69], v[128:129], v[136:137]
	v_pk_fma_f32 v[234:235], v[70:71], v[130:131], v[138:139]
	v_pk_fma_f32 v[240:241], v[72:73], v[144:145], v[152:153]
	v_pk_fma_f32 v[248:249], v[74:75], v[146:147], v[154:155]
	v_pk_fma_f32 v[220:221], v[64:65], v[144:145], v[152:153]
	v_pk_fma_f32 v[230:231], v[66:67], v[146:147], v[154:155]
	v_fmac_f32_dpp v226, v250, v124 row_ror:1 row_mask:0xf bank_mask:0xf bound_ctrl:1
	v_fmac_f32_dpp v244, v210, v126 row_ror:1 row_mask:0xf bank_mask:0xf bound_ctrl:1
	v_fmac_f32_dpp v214, v204, v124 row_ror:1 row_mask:0xf bank_mask:0xf bound_ctrl:1
	v_fmac_f32_dpp v234, v224, v126 row_ror:1 row_mask:0xf bank_mask:0xf bound_ctrl:1
	v_fmac_f32_dpp v227, v251, v125 row_ror:1 row_mask:0xf bank_mask:0xf bound_ctrl:1
	v_fmac_f32_dpp v245, v211, v127 row_ror:1 row_mask:0xf bank_mask:0xf bound_ctrl:1
	v_fmac_f32_dpp v215, v205, v125 row_ror:1 row_mask:0xf bank_mask:0xf bound_ctrl:1
	v_fmac_f32_dpp v235, v225, v127 row_ror:1 row_mask:0xf bank_mask:0xf bound_ctrl:1
	v_fmac_f32_dpp v240, v212, v140 row_ror:1 row_mask:0xf bank_mask:0xf bound_ctrl:1
	v_fmac_f32_dpp v248, v222, v142 row_ror:1 row_mask:0xf bank_mask:0xf bound_ctrl:1
	v_fmac_f32_dpp v220, v206, v140 row_ror:1 row_mask:0xf bank_mask:0xf bound_ctrl:1
	v_fmac_f32_dpp v230, v232, v142 row_ror:1 row_mask:0xf bank_mask:0xf bound_ctrl:1
	v_fmac_f32_dpp v241, v213, v141 row_ror:1 row_mask:0xf bank_mask:0xf bound_ctrl:1
	v_fmac_f32_dpp v249, v223, v143 row_ror:1 row_mask:0xf bank_mask:0xf bound_ctrl:1
	v_fmac_f32_dpp v221, v207, v141 row_ror:1 row_mask:0xf bank_mask:0xf bound_ctrl:1
	v_fmac_f32_dpp v231, v233, v143 row_ror:1 row_mask:0xf bank_mask:0xf bound_ctrl:1
	v_cndmask_b32_e64 v250, v76, v68, s[34:35]
	v_cndmask_b32_e64 v210, v78, v70, s[34:35]
	v_fmac_f32_dpp v214, v68, v132 row_shl:1 row_mask:0xf bank_mask:0xf bound_ctrl:1
	v_fmac_f32_dpp v234, v70, v134 row_shl:1 row_mask:0xf bank_mask:0xf bound_ctrl:1
	v_cndmask_b32_e64 v251, v77, v69, s[34:35]
	v_cndmask_b32_e64 v211, v79, v71, s[34:35]
	v_fmac_f32_dpp v215, v69, v133 row_shl:1 row_mask:0xf bank_mask:0xf bound_ctrl:1
	v_fmac_f32_dpp v235, v71, v135 row_shl:1 row_mask:0xf bank_mask:0xf bound_ctrl:1
	v_cndmask_b32_e64 v212, v72, v64, s[34:35]
	v_cndmask_b32_e64 v222, v74, v66, s[34:35]
	v_fmac_f32_dpp v220, v64, v148 row_shl:1 row_mask:0xf bank_mask:0xf bound_ctrl:1
	v_fmac_f32_dpp v230, v66, v150 row_shl:1 row_mask:0xf bank_mask:0xf bound_ctrl:1
	v_cndmask_b32_e64 v213, v73, v65, s[34:35]
	v_cndmask_b32_e64 v223, v75, v67, s[34:35]
	v_fmac_f32_dpp v221, v65, v149 row_shl:1 row_mask:0xf bank_mask:0xf bound_ctrl:1
	v_fmac_f32_dpp v231, v67, v151 row_shl:1 row_mask:0xf bank_mask:0xf bound_ctrl:1
	v_fmac_f32_dpp v226, v250, v132 row_ror:15 row_mask:0xf bank_mask:0xf
	v_fmac_f32_dpp v244, v210, v134 row_ror:15 row_mask:0xf bank_mask:0xf
	v_pk_mul_f32 v[204:205], v[254:255], v[214:215]
	v_pk_mul_f32 v[224:225], v[254:255], v[234:235]
	v_fmac_f32_dpp v227, v251, v133 row_ror:15 row_mask:0xf bank_mask:0xf
	v_fmac_f32_dpp v245, v211, v135 row_ror:15 row_mask:0xf bank_mask:0xf
	v_exp_f32_e32 v204, v204
	v_exp_f32_e32 v224, v224
	v_fmac_f32_dpp v240, v212, v148 row_ror:15 row_mask:0xf bank_mask:0xf
	v_fmac_f32_dpp v248, v222, v150 row_ror:15 row_mask:0xf bank_mask:0xf
	v_exp_f32_e32 v205, v205
	v_exp_f32_e32 v225, v225
	v_fmac_f32_dpp v241, v213, v149 row_ror:15 row_mask:0xf bank_mask:0xf
	v_fmac_f32_dpp v249, v223, v151 row_ror:15 row_mask:0xf bank_mask:0xf
	v_pk_add_f32 v[204:205], v[204:205], v[252:253]
	v_pk_add_f32 v[224:225], v[224:225], v[252:253]
	v_pk_mul_f32 v[250:251], v[254:255], v[226:227]
	v_pk_mul_f32 v[210:211], v[254:255], v[244:245]
	v_rcp_f32_e32 v204, v204
	v_rcp_f32_e32 v224, v224
	v_exp_f32_e32 v250, v250
	v_exp_f32_e32 v210, v210
	v_rcp_f32_e32 v205, v205
	v_rcp_f32_e32 v225, v225
	v_exp_f32_e32 v251, v251
	v_exp_f32_e32 v211, v211
	v_pk_mul_f32 v[214:215], v[214:215], v[204:205]
	v_pk_mul_f32 v[234:235], v[234:235], v[224:225]
	v_pk_add_f32 v[250:251], v[250:251], v[252:253]
	v_pk_add_f32 v[210:211], v[210:211], v[252:253]
	v_pk_mul_f32 v[220:221], v[220:221], v[214:215]
	v_pk_mul_f32 v[230:231], v[230:231], v[234:235]
	v_rcp_f32_e32 v250, v250
	v_rcp_f32_e32 v210, v210
	v_rcp_f32_e32 v251, v251
	v_rcp_f32_e32 v211, v211
	v_pk_mul_f32 v[226:227], v[226:227], v[250:251]
	v_pk_mul_f32 v[244:245], v[244:245], v[210:211]
	v_pk_mul_f32 v[240:241], v[240:241], v[226:227]
	v_pk_mul_f32 v[248:249], v[248:249], v[244:245]
	v_cvt_pk_bf16_f32 v88, v228, v229
	v_cvt_pk_bf16_f32 v89, v242, v243
	s_nop 0
	s_nop 0
	s_nop 0
	s_nop 0
	s_nop 0
	v_cvt_pk_bf16_f32 v80, v240, v241
	v_cvt_pk_bf16_f32 v81, v248, v249
	s_nop 0
	s_nop 0
	s_nop 0
	s_nop 0
	s_nop 0
	v_cvt_pk_bf16_f32 v72, v220, v221
	v_cvt_pk_bf16_f32 v73, v230, v231
	s_and_saveexec_b64 s[40:41], s[38:39]
	s_cbranch_execz .LBB0_1413
	v_mov_b32_e32 v181, v165
	v_lshl_add_u64 v[74:75], s[10:11], 0, v[180:181]
	v_mov_b64_e32 v[76:77], s[0:1]
	s_movk_i32 s48, 0x2c00
	v_mad_u64_u32 v[76:77], s[86:87], v74, s48, v[76:77]
	v_mad_i32_i24 v77, v75, s48, v77
	v_lshl_add_u64 v[74:75], s[16:17], 1, v[76:77]
	s_lshl_b32 s48, s5, 1
	v_lshl_add_u64 v[74:75], v[74:75], 0, s[48:49]
	v_mov_b32_e32 v179, v165
	s_movk_i32 s66, 0x2c00
	v_lshl_add_u64 v[74:75], v[74:75], 0, v[178:179]
	v_cvt_pk_bf16_f32 v68, v68, v69
	v_cvt_pk_bf16_f32 v69, v70, v71
	global_store_dwordx2 v[74:75], v[68:69], off
	v_cvt_pk_bf16_f32 v64, v64, v65
	v_cvt_pk_bf16_f32 v65, v66, v67
	global_store_dwordx2 v[74:75], v[64:65], off offset:256
.LBB0_1413:
	s_or_b64 exec, exec, s[40:41]
	v_or_b32_e32 v68, 4, v182
	v_ashrrev_i32_e32 v69, 31, v68
	v_lshlrev_b64 v[82:83], 2, v[68:69]
	global_load_dwordx4 v[64:67], v[184:185], off offset:16
	v_lshl_add_u64 v[68:69], s[58:59], 0, v[82:83]
	global_load_dwordx4 v[68:71], v[68:69], off
	v_lshl_add_u64 v[74:75], s[60:61], 0, v[82:83]
	global_load_dwordx4 v[74:77], v[74:75], off
	s_nop 0
	global_load_dwordx4 v[84:87], v[186:187], off offset:16
	v_lshl_add_u64 v[90:91], s[12:13], 0, v[82:83]
	global_load_dwordx4 v[92:95], v[90:91], off
	v_lshl_add_u64 v[90:91], s[50:51], 0, v[82:83]
	global_load_dwordx4 v[100:103], v[90:91], off
	v_lshl_add_u64 v[90:91], s[20:21], 0, v[82:83]
	global_load_dwordx4 v[108:111], v[90:91], off
	v_lshl_add_u64 v[82:83], s[44:45], 0, v[82:83]
	global_load_dwordx4 v[122:125], v[82:83], off
	s_nop 0
	v_mov_b32_e32 v106, v165
	s_ashr_i32 s40, s6, 6
	s_ashr_i32 s41, s40, 31
	s_ashr_i32 s31, s31, 8
	s_lshl_b64 s[40:41], s[40:41], 15
	v_or_b32_e32 v78, s7, v200
	v_mov_b32_e32 v107, v165
	s_add_u32 s86, s80, s40
	s_mul_hi_i32 s7, s31, 0x160000
	s_mul_i32 s31, s31, 0x160000
	v_and_b32_e32 v82, 56, v182
	v_lshlrev_b32_e32 v78, 6, v78
	s_movk_i32 s6, 0x33c0
	s_addc_u32 s87, s81, s41
	v_and_or_b32 v78, v78, s6, v82
	s_add_u32 s40, s86, s31
	s_addc_u32 s41, s87, s7
	v_lshlrev_b32_e32 v164, 1, v78
	s_waitcnt vmcnt(0)
	v_pk_fma_f32 v[250:251], v[60:61], v[68:69], v[84:85]
	v_pk_fma_f32 v[222:223], v[62:63], v[70:71], v[86:87]
	v_cndmask_b32_e64 v204, v52, v60, vcc
	v_cndmask_b32_e64 v232, v54, v62, vcc
	v_pk_fma_f32 v[212:213], v[56:57], v[100:101], v[122:123]
	v_pk_fma_f32 v[244:245], v[58:59], v[102:103], v[124:125]
	v_cndmask_b32_e64 v205, v53, v61, vcc
	v_cndmask_b32_e64 v233, v55, v63, vcc
	v_fmac_f32_dpp v250, v60, v64 row_shr:1 row_mask:0xf bank_mask:0xf bound_ctrl:1
	v_fmac_f32_dpp v222, v62, v66 row_shr:1 row_mask:0xf bank_mask:0xf bound_ctrl:1
	v_cndmask_b32_e64 v206, v48, v56, vcc
	v_cndmask_b32_e64 v234, v50, v58, vcc
	v_fmac_f32_dpp v251, v61, v65 row_shr:1 row_mask:0xf bank_mask:0xf bound_ctrl:1
	v_fmac_f32_dpp v223, v63, v67 row_shr:1 row_mask:0xf bank_mask:0xf bound_ctrl:1
	v_cndmask_b32_e64 v207, v49, v57, vcc
	v_cndmask_b32_e64 v235, v51, v59, vcc
	v_fmac_f32_dpp v212, v56, v92 row_shr:1 row_mask:0xf bank_mask:0xf bound_ctrl:1
	v_fmac_f32_dpp v244, v58, v94 row_shr:1 row_mask:0xf bank_mask:0xf bound_ctrl:1
	v_pk_fma_f32 v[214:215], v[52:53], v[68:69], v[84:85]
	v_pk_fma_f32 v[228:229], v[54:55], v[70:71], v[86:87]
	v_fmac_f32_dpp v213, v57, v93 row_shr:1 row_mask:0xf bank_mask:0xf bound_ctrl:1
	v_fmac_f32_dpp v245, v59, v95 row_shr:1 row_mask:0xf bank_mask:0xf bound_ctrl:1
	v_pk_fma_f32 v[224:225], v[48:49], v[100:101], v[122:123]
	v_pk_fma_f32 v[242:243], v[50:51], v[102:103], v[124:125]
	v_cndmask_b32_e64 v246, v60, v52, s[34:35]
	v_cndmask_b32_e64 v226, v62, v54, s[34:35]
	v_fmac_f32_dpp v214, v204, v64 row_ror:1 row_mask:0xf bank_mask:0xf bound_ctrl:1
	v_fmac_f32_dpp v228, v232, v66 row_ror:1 row_mask:0xf bank_mask:0xf bound_ctrl:1
	v_cndmask_b32_e64 v247, v61, v53, s[34:35]
	v_cndmask_b32_e64 v227, v63, v55, s[34:35]
	v_fmac_f32_dpp v215, v205, v65 row_ror:1 row_mask:0xf bank_mask:0xf bound_ctrl:1
	v_fmac_f32_dpp v229, v233, v67 row_ror:1 row_mask:0xf bank_mask:0xf bound_ctrl:1
	v_cndmask_b32_e64 v208, v56, v48, s[34:35]
	v_cndmask_b32_e64 v210, v58, v50, s[34:35]
	v_fmac_f32_dpp v224, v206, v92 row_ror:1 row_mask:0xf bank_mask:0xf bound_ctrl:1
	v_fmac_f32_dpp v242, v234, v94 row_ror:1 row_mask:0xf bank_mask:0xf bound_ctrl:1
	v_cndmask_b32_e64 v209, v57, v49, s[34:35]
	v_cndmask_b32_e64 v211, v59, v51, s[34:35]
	v_fmac_f32_dpp v225, v207, v93 row_ror:1 row_mask:0xf bank_mask:0xf bound_ctrl:1
	v_fmac_f32_dpp v243, v235, v95 row_ror:1 row_mask:0xf bank_mask:0xf bound_ctrl:1
	v_fmac_f32_dpp v250, v246, v74 row_ror:15 row_mask:0xf bank_mask:0xf
	v_fmac_f32_dpp v222, v226, v76 row_ror:15 row_mask:0xf bank_mask:0xf
	v_cndmask_b32_e64 v204, v52, v44, s[34:35]
	v_cndmask_b32_e64 v232, v54, v46, s[34:35]
	v_fmac_f32_dpp v251, v247, v75 row_ror:15 row_mask:0xf bank_mask:0xf
	v_fmac_f32_dpp v223, v227, v77 row_ror:15 row_mask:0xf bank_mask:0xf
	v_cndmask_b32_e64 v205, v53, v45, s[34:35]
	v_cndmask_b32_e64 v233, v55, v47, s[34:35]
	v_fmac_f32_dpp v212, v208, v108 row_ror:15 row_mask:0xf bank_mask:0xf
	v_fmac_f32_dpp v244, v210, v110 row_ror:15 row_mask:0xf bank_mask:0xf
	v_cndmask_b32_e64 v206, v48, v40, s[34:35]
	v_cndmask_b32_e64 v234, v50, v42, s[34:35]
	v_fmac_f32_dpp v213, v209, v109 row_ror:15 row_mask:0xf bank_mask:0xf
	v_fmac_f32_dpp v245, v211, v111 row_ror:15 row_mask:0xf bank_mask:0xf
	v_cndmask_b32_e64 v207, v49, v41, s[34:35]
	v_cndmask_b32_e64 v235, v51, v43, s[34:35]
	v_pk_mul_f32 v[246:247], v[254:255], v[250:251]
	v_pk_mul_f32 v[226:227], v[254:255], v[222:223]
	v_fmac_f32_dpp v214, v204, v74 row_ror:15 row_mask:0xf bank_mask:0xf
	v_fmac_f32_dpp v228, v232, v76 row_ror:15 row_mask:0xf bank_mask:0xf
	v_exp_f32_e32 v246, v246
	v_exp_f32_e32 v226, v226
	v_fmac_f32_dpp v215, v205, v75 row_ror:15 row_mask:0xf bank_mask:0xf
	v_fmac_f32_dpp v229, v233, v77 row_ror:15 row_mask:0xf bank_mask:0xf
	v_exp_f32_e32 v247, v247
	v_exp_f32_e32 v227, v227
	v_fmac_f32_dpp v224, v206, v108 row_ror:15 row_mask:0xf bank_mask:0xf
	v_fmac_f32_dpp v242, v234, v110 row_ror:15 row_mask:0xf bank_mask:0xf
	v_pk_add_f32 v[246:247], v[246:247], v[252:253]
	v_pk_add_f32 v[226:227], v[226:227], v[252:253]
	v_fmac_f32_dpp v225, v207, v109 row_ror:15 row_mask:0xf bank_mask:0xf
	v_fmac_f32_dpp v243, v235, v111 row_ror:15 row_mask:0xf bank_mask:0xf
	v_rcp_f32_e32 v246, v246
	v_rcp_f32_e32 v226, v226
	v_pk_mul_f32 v[204:205], v[254:255], v[214:215]
	v_pk_mul_f32 v[232:233], v[254:255], v[228:229]
	v_rcp_f32_e32 v247, v247
	v_rcp_f32_e32 v227, v227
	v_exp_f32_e32 v204, v204
	v_exp_f32_e32 v232, v232
	v_pk_mul_f32 v[250:251], v[250:251], v[246:247]
	v_pk_mul_f32 v[222:223], v[222:223], v[226:227]
	v_exp_f32_e32 v205, v205
	v_exp_f32_e32 v233, v233
	v_pk_mul_f32 v[212:213], v[212:213], v[250:251]
	v_pk_mul_f32 v[244:245], v[244:245], v[222:223]
	v_pk_add_f32 v[204:205], v[204:205], v[252:253]
	v_pk_add_f32 v[232:233], v[232:233], v[252:253]
	v_rcp_f32_e32 v204, v204
	v_rcp_f32_e32 v232, v232
	v_rcp_f32_e32 v205, v205
	v_rcp_f32_e32 v233, v233
	v_pk_mul_f32 v[214:215], v[214:215], v[204:205]
	v_pk_mul_f32 v[228:229], v[228:229], v[232:233]
	v_pk_mul_f32 v[224:225], v[224:225], v[214:215]
	v_pk_mul_f32 v[242:243], v[242:243], v[228:229]
	s_nop 1
	v_cvt_pk_bf16_f32 v120, v212, v213
	v_cvt_pk_bf16_f32 v121, v244, v245
	global_store_dwordx4 v164, v[118:121], s[40:41]
	s_and_saveexec_b64 s[6:7], s[36:37]
	s_cbranch_execz .LBB0_1415
	v_mov_b64_e32 v[78:79], s[0:1]
	v_mad_i64_i32 v[78:79], s[88:89], v183, s66, v[78:79]
	v_lshl_add_u64 v[78:79], s[16:17], 1, v[78:79]
	s_lshl_b32 s48, s5, 1
	v_lshl_add_u64 v[78:79], v[78:79], 0, s[48:49]
	v_mov_b32_e32 v179, v165
	v_lshl_add_u64 v[78:79], v[78:79], 0, v[178:179]
	v_cvt_pk_bf16_f32 v90, v60, v61
	v_cvt_pk_bf16_f32 v91, v62, v63
	global_store_dwordx2 v[78:79], v[90:91], off offset:8
	v_cvt_pk_bf16_f32 v90, v56, v57
	v_cvt_pk_bf16_f32 v91, v58, v59
	global_store_dwordx2 v[78:79], v[90:91], off offset:264
.LBB0_1415:
	s_or_b64 exec, exec, s[6:7]
	s_nop 0
	s_nop 0
	s_nop 0
	s_nop 0
	v_cndmask_b32_e64 v240, v44, v52, vcc
	v_cndmask_b32_e64 v246, v46, v54, vcc
	v_cndmask_b32_e64 v210, v36, v44, vcc
	v_cndmask_b32_e64 v214, v38, v46, vcc
	v_cndmask_b32_e64 v241, v45, v53, vcc
	v_cndmask_b32_e64 v247, v47, v55, vcc
	v_cndmask_b32_e64 v211, v37, v45, vcc
	v_cndmask_b32_e64 v215, v39, v47, vcc
	v_cndmask_b32_e64 v248, v40, v48, vcc
	v_cndmask_b32_e64 v208, v42, v50, vcc
	v_cndmask_b32_e64 v222, v32, v40, vcc
	v_cndmask_b32_e64 v232, v34, v42, vcc
	v_cndmask_b32_e64 v249, v41, v49, vcc
	v_cndmask_b32_e64 v209, v43, v51, vcc
	v_cndmask_b32_e64 v223, v33, v41, vcc
	v_cndmask_b32_e64 v233, v35, v43, vcc
	v_pk_fma_f32 v[220:221], v[44:45], v[68:69], v[84:85]
	v_pk_fma_f32 v[250:251], v[46:47], v[70:71], v[86:87]
	v_pk_fma_f32 v[204:205], v[36:37], v[68:69], v[84:85]
	v_pk_fma_f32 v[234:235], v[38:39], v[70:71], v[86:87]
	v_pk_fma_f32 v[230:231], v[40:41], v[100:101], v[122:123]
	v_pk_fma_f32 v[226:227], v[42:43], v[102:103], v[124:125]
	v_pk_fma_f32 v[206:207], v[32:33], v[100:101], v[122:123]
	v_pk_fma_f32 v[228:229], v[34:35], v[102:103], v[124:125]
	v_fmac_f32_dpp v220, v240, v64 row_ror:1 row_mask:0xf bank_mask:0xf bound_ctrl:1
	v_fmac_f32_dpp v250, v246, v66 row_ror:1 row_mask:0xf bank_mask:0xf bound_ctrl:1
	v_fmac_f32_dpp v204, v210, v64 row_ror:1 row_mask:0xf bank_mask:0xf bound_ctrl:1
	v_fmac_f32_dpp v234, v214, v66 row_ror:1 row_mask:0xf bank_mask:0xf bound_ctrl:1
	v_fmac_f32_dpp v221, v241, v65 row_ror:1 row_mask:0xf bank_mask:0xf bound_ctrl:1
	v_fmac_f32_dpp v251, v247, v67 row_ror:1 row_mask:0xf bank_mask:0xf bound_ctrl:1
	v_fmac_f32_dpp v205, v211, v65 row_ror:1 row_mask:0xf bank_mask:0xf bound_ctrl:1
	v_fmac_f32_dpp v235, v215, v67 row_ror:1 row_mask:0xf bank_mask:0xf bound_ctrl:1
	v_fmac_f32_dpp v230, v248, v92 row_ror:1 row_mask:0xf bank_mask:0xf bound_ctrl:1
	v_fmac_f32_dpp v226, v208, v94 row_ror:1 row_mask:0xf bank_mask:0xf bound_ctrl:1
	v_fmac_f32_dpp v206, v222, v92 row_ror:1 row_mask:0xf bank_mask:0xf bound_ctrl:1
	v_fmac_f32_dpp v228, v232, v94 row_ror:1 row_mask:0xf bank_mask:0xf bound_ctrl:1
	v_fmac_f32_dpp v231, v249, v93 row_ror:1 row_mask:0xf bank_mask:0xf bound_ctrl:1
	v_fmac_f32_dpp v227, v209, v95 row_ror:1 row_mask:0xf bank_mask:0xf bound_ctrl:1
	v_fmac_f32_dpp v207, v223, v93 row_ror:1 row_mask:0xf bank_mask:0xf bound_ctrl:1
	v_fmac_f32_dpp v229, v233, v95 row_ror:1 row_mask:0xf bank_mask:0xf bound_ctrl:1
	v_cndmask_b32_e64 v240, v44, v36, s[34:35]
	v_cndmask_b32_e64 v246, v46, v38, s[34:35]
	v_fmac_f32_dpp v204, v36, v74 row_shl:1 row_mask:0xf bank_mask:0xf bound_ctrl:1
	v_fmac_f32_dpp v234, v38, v76 row_shl:1 row_mask:0xf bank_mask:0xf bound_ctrl:1
	v_cndmask_b32_e64 v241, v45, v37, s[34:35]
	v_cndmask_b32_e64 v247, v47, v39, s[34:35]
	v_fmac_f32_dpp v205, v37, v75 row_shl:1 row_mask:0xf bank_mask:0xf bound_ctrl:1
	v_fmac_f32_dpp v235, v39, v77 row_shl:1 row_mask:0xf bank_mask:0xf bound_ctrl:1
	v_cndmask_b32_e64 v248, v40, v32, s[34:35]
	v_cndmask_b32_e64 v208, v42, v34, s[34:35]
	v_fmac_f32_dpp v206, v32, v108 row_shl:1 row_mask:0xf bank_mask:0xf bound_ctrl:1
	v_fmac_f32_dpp v228, v34, v110 row_shl:1 row_mask:0xf bank_mask:0xf bound_ctrl:1
	v_cndmask_b32_e64 v249, v41, v33, s[34:35]
	v_cndmask_b32_e64 v209, v43, v35, s[34:35]
	v_fmac_f32_dpp v207, v33, v109 row_shl:1 row_mask:0xf bank_mask:0xf bound_ctrl:1
	v_fmac_f32_dpp v229, v35, v111 row_shl:1 row_mask:0xf bank_mask:0xf bound_ctrl:1
	v_fmac_f32_dpp v220, v240, v74 row_ror:15 row_mask:0xf bank_mask:0xf
	v_fmac_f32_dpp v250, v246, v76 row_ror:15 row_mask:0xf bank_mask:0xf
	v_pk_mul_f32 v[210:211], v[254:255], v[204:205]
	v_pk_mul_f32 v[214:215], v[254:255], v[234:235]
	v_fmac_f32_dpp v221, v241, v75 row_ror:15 row_mask:0xf bank_mask:0xf
	v_fmac_f32_dpp v251, v247, v77 row_ror:15 row_mask:0xf bank_mask:0xf
	v_exp_f32_e32 v210, v210
	v_exp_f32_e32 v214, v214
	v_fmac_f32_dpp v230, v248, v108 row_ror:15 row_mask:0xf bank_mask:0xf
	v_fmac_f32_dpp v226, v208, v110 row_ror:15 row_mask:0xf bank_mask:0xf
	v_exp_f32_e32 v211, v211
	v_exp_f32_e32 v215, v215
	v_fmac_f32_dpp v231, v249, v109 row_ror:15 row_mask:0xf bank_mask:0xf
	v_fmac_f32_dpp v227, v209, v111 row_ror:15 row_mask:0xf bank_mask:0xf
	v_pk_add_f32 v[210:211], v[210:211], v[252:253]
	v_pk_add_f32 v[214:215], v[214:215], v[252:253]
	v_pk_mul_f32 v[240:241], v[254:255], v[220:221]
	v_pk_mul_f32 v[246:247], v[254:255], v[250:251]
	v_rcp_f32_e32 v210, v210
	v_rcp_f32_e32 v214, v214
	v_exp_f32_e32 v240, v240
	v_exp_f32_e32 v246, v246
	v_rcp_f32_e32 v211, v211
	v_rcp_f32_e32 v215, v215
	v_exp_f32_e32 v241, v241
	v_exp_f32_e32 v247, v247
	v_pk_mul_f32 v[204:205], v[204:205], v[210:211]
	v_pk_mul_f32 v[234:235], v[234:235], v[214:215]
	v_pk_add_f32 v[240:241], v[240:241], v[252:253]
	v_pk_add_f32 v[246:247], v[246:247], v[252:253]
	v_pk_mul_f32 v[206:207], v[206:207], v[204:205]
	v_pk_mul_f32 v[228:229], v[228:229], v[234:235]
	v_rcp_f32_e32 v240, v240
	v_rcp_f32_e32 v246, v246
	v_rcp_f32_e32 v241, v241
	v_rcp_f32_e32 v247, v247
	v_pk_mul_f32 v[220:221], v[220:221], v[240:241]
	v_pk_mul_f32 v[250:251], v[250:251], v[246:247]
	v_pk_mul_f32 v[230:231], v[230:231], v[220:221]
	v_pk_mul_f32 v[226:227], v[226:227], v[250:251]
	s_nop 0
	s_nop 0
	v_cvt_pk_bf16_f32 v118, v224, v225
	s_nop 0
	v_cvt_pk_bf16_f32 v119, v242, v243
	s_nop 0
	s_nop 0
	s_nop 0
	v_cvt_pk_bf16_f32 v115, v226, v227
	s_nop 0
	s_nop 0
	s_nop 0
	v_lshl_add_u64 v[78:79], s[40:41], 0, v[164:165]
	s_movk_i32 s6, 0x1000
	v_cvt_pk_bf16_f32 v114, v230, v231
	v_add_co_u32_e64 v48, s[40:41], s6, v78
	s_nop 0
	s_nop 0
	v_addc_co_u32_e64 v49, s[40:41], 0, v79, s[40:41]
	global_store_dwordx4 v[78:79], v[116:119], off offset:2048
	global_store_dwordx4 v[48:49], v[112:115], off
	v_cvt_pk_bf16_f32 v106, v206, v207
	v_cvt_pk_bf16_f32 v107, v228, v229
	global_store_dwordx4 v[48:49], v[104:107], off offset:2048
	s_and_saveexec_b64 s[40:41], s[38:39]
	s_cbranch_execz .LBB0_1417
	v_mov_b32_e32 v181, v165
	v_lshl_add_u64 v[40:41], s[52:53], 0, v[180:181]
	v_mov_b64_e32 v[42:43], s[0:1]
	s_movk_i32 s31, 0x2c00
	v_mad_u64_u32 v[42:43], s[6:7], v40, s31, v[42:43]
	v_mad_i32_i24 v43, v41, s31, v43
	v_lshl_add_u64 v[40:41], s[16:17], 1, v[42:43]
	s_lshl_b32 s48, s5, 1
	v_lshl_add_u64 v[40:41], v[40:41], 0, s[48:49]
	v_mov_b32_e32 v179, v165
	s_movk_i32 s66, 0x2c00
	v_lshl_add_u64 v[40:41], v[40:41], 0, v[178:179]
	v_cvt_pk_bf16_f32 v36, v36, v37
	v_cvt_pk_bf16_f32 v37, v38, v39
	global_store_dwordx2 v[40:41], v[36:37], off offset:8
	v_cvt_pk_bf16_f32 v32, v32, v33
	v_cvt_pk_bf16_f32 v33, v34, v35
	global_store_dwordx2 v[40:41], v[32:33], off offset:264
.LBB0_1417:
	s_or_b64 exec, exec, s[40:41]
	v_pk_fma_f32 v[240:241], v[28:29], v[68:69], v[84:85]
	v_pk_fma_f32 v[208:209], v[30:31], v[70:71], v[86:87]
	v_cndmask_b32_e64 v210, v20, v28, vcc
	v_cndmask_b32_e64 v232, v22, v30, vcc
	v_pk_fma_f32 v[248:249], v[24:25], v[100:101], v[122:123]
	v_pk_fma_f32 v[250:251], v[26:27], v[102:103], v[124:125]
	v_cndmask_b32_e64 v211, v21, v29, vcc
	v_cndmask_b32_e64 v233, v23, v31, vcc
	v_fmac_f32_dpp v240, v28, v64 row_shr:1 row_mask:0xf bank_mask:0xf bound_ctrl:1
	v_fmac_f32_dpp v208, v30, v66 row_shr:1 row_mask:0xf bank_mask:0xf bound_ctrl:1
	v_cndmask_b32_e64 v222, v16, v24, vcc
	v_cndmask_b32_e64 v234, v18, v26, vcc
	v_fmac_f32_dpp v241, v29, v65 row_shr:1 row_mask:0xf bank_mask:0xf bound_ctrl:1
	v_fmac_f32_dpp v209, v31, v67 row_shr:1 row_mask:0xf bank_mask:0xf bound_ctrl:1
	v_cndmask_b32_e64 v223, v17, v25, vcc
	v_cndmask_b32_e64 v235, v19, v27, vcc
	v_fmac_f32_dpp v248, v24, v92 row_shr:1 row_mask:0xf bank_mask:0xf bound_ctrl:1
	v_fmac_f32_dpp v250, v26, v94 row_shr:1 row_mask:0xf bank_mask:0xf bound_ctrl:1
	v_pk_fma_f32 v[204:205], v[20:21], v[68:69], v[84:85]
	v_pk_fma_f32 v[224:225], v[22:23], v[70:71], v[86:87]
	v_fmac_f32_dpp v249, v25, v93 row_shr:1 row_mask:0xf bank_mask:0xf bound_ctrl:1
	v_fmac_f32_dpp v251, v27, v95 row_shr:1 row_mask:0xf bank_mask:0xf bound_ctrl:1
	v_pk_fma_f32 v[214:215], v[16:17], v[100:101], v[122:123]
	v_pk_fma_f32 v[242:243], v[18:19], v[102:103], v[124:125]
	v_cndmask_b32_e64 v212, v28, v20, s[34:35]
	v_cndmask_b32_e64 v220, v30, v22, s[34:35]
	v_fmac_f32_dpp v204, v210, v64 row_ror:1 row_mask:0xf bank_mask:0xf bound_ctrl:1
	v_fmac_f32_dpp v224, v232, v66 row_ror:1 row_mask:0xf bank_mask:0xf bound_ctrl:1
	v_cndmask_b32_e64 v213, v29, v21, s[34:35]
	v_cndmask_b32_e64 v221, v31, v23, s[34:35]
	v_fmac_f32_dpp v205, v211, v65 row_ror:1 row_mask:0xf bank_mask:0xf bound_ctrl:1
	v_fmac_f32_dpp v225, v233, v67 row_ror:1 row_mask:0xf bank_mask:0xf bound_ctrl:1
	v_cndmask_b32_e64 v244, v24, v16, s[34:35]
	v_cndmask_b32_e64 v246, v26, v18, s[34:35]
	v_fmac_f32_dpp v214, v222, v92 row_ror:1 row_mask:0xf bank_mask:0xf bound_ctrl:1
	v_fmac_f32_dpp v242, v234, v94 row_ror:1 row_mask:0xf bank_mask:0xf bound_ctrl:1
	v_cndmask_b32_e64 v245, v25, v17, s[34:35]
	v_cndmask_b32_e64 v247, v27, v19, s[34:35]
	v_fmac_f32_dpp v215, v223, v93 row_ror:1 row_mask:0xf bank_mask:0xf bound_ctrl:1
	v_fmac_f32_dpp v243, v235, v95 row_ror:1 row_mask:0xf bank_mask:0xf bound_ctrl:1
	v_fmac_f32_dpp v240, v212, v74 row_ror:15 row_mask:0xf bank_mask:0xf
	v_fmac_f32_dpp v208, v220, v76 row_ror:15 row_mask:0xf bank_mask:0xf
	v_cndmask_b32_e64 v210, v20, v12, s[34:35]
	v_cndmask_b32_e64 v232, v22, v14, s[34:35]
	v_fmac_f32_dpp v241, v213, v75 row_ror:15 row_mask:0xf bank_mask:0xf
	v_fmac_f32_dpp v209, v221, v77 row_ror:15 row_mask:0xf bank_mask:0xf
	v_cndmask_b32_e64 v211, v21, v13, s[34:35]
	v_cndmask_b32_e64 v233, v23, v15, s[34:35]
	v_fmac_f32_dpp v248, v244, v108 row_ror:15 row_mask:0xf bank_mask:0xf
	v_fmac_f32_dpp v250, v246, v110 row_ror:15 row_mask:0xf bank_mask:0xf
	v_cndmask_b32_e64 v222, v16, v8, s[34:35]
	v_cndmask_b32_e64 v234, v18, v10, s[34:35]
	v_fmac_f32_dpp v249, v245, v109 row_ror:15 row_mask:0xf bank_mask:0xf
	v_fmac_f32_dpp v251, v247, v111 row_ror:15 row_mask:0xf bank_mask:0xf
	v_cndmask_b32_e64 v223, v17, v9, s[34:35]
	v_cndmask_b32_e64 v235, v19, v11, s[34:35]
	v_pk_mul_f32 v[212:213], v[254:255], v[240:241]
	v_pk_mul_f32 v[220:221], v[254:255], v[208:209]
	v_fmac_f32_dpp v204, v210, v74 row_ror:15 row_mask:0xf bank_mask:0xf
	v_fmac_f32_dpp v224, v232, v76 row_ror:15 row_mask:0xf bank_mask:0xf
	v_exp_f32_e32 v212, v212
	v_exp_f32_e32 v220, v220
	v_fmac_f32_dpp v205, v211, v75 row_ror:15 row_mask:0xf bank_mask:0xf
	v_fmac_f32_dpp v225, v233, v77 row_ror:15 row_mask:0xf bank_mask:0xf
	v_exp_f32_e32 v213, v213
	v_exp_f32_e32 v221, v221
	v_fmac_f32_dpp v214, v222, v108 row_ror:15 row_mask:0xf bank_mask:0xf
	v_fmac_f32_dpp v242, v234, v110 row_ror:15 row_mask:0xf bank_mask:0xf
	v_pk_add_f32 v[212:213], v[212:213], v[252:253]
	v_pk_add_f32 v[220:221], v[220:221], v[252:253]
	v_fmac_f32_dpp v215, v223, v109 row_ror:15 row_mask:0xf bank_mask:0xf
	v_fmac_f32_dpp v243, v235, v111 row_ror:15 row_mask:0xf bank_mask:0xf
	v_rcp_f32_e32 v212, v212
	v_rcp_f32_e32 v220, v220
	v_pk_mul_f32 v[210:211], v[254:255], v[204:205]
	v_pk_mul_f32 v[232:233], v[254:255], v[224:225]
	v_rcp_f32_e32 v213, v213
	v_rcp_f32_e32 v221, v221
	v_exp_f32_e32 v210, v210
	v_exp_f32_e32 v232, v232
	v_pk_mul_f32 v[240:241], v[240:241], v[212:213]
	v_pk_mul_f32 v[208:209], v[208:209], v[220:221]
	v_exp_f32_e32 v211, v211
	v_exp_f32_e32 v233, v233
	v_pk_mul_f32 v[248:249], v[248:249], v[240:241]
	v_pk_mul_f32 v[250:251], v[250:251], v[208:209]
	v_pk_add_f32 v[210:211], v[210:211], v[252:253]
	v_pk_add_f32 v[232:233], v[232:233], v[252:253]
	v_rcp_f32_e32 v210, v210
	v_rcp_f32_e32 v232, v232
	v_rcp_f32_e32 v211, v211
	v_rcp_f32_e32 v233, v233
	v_pk_mul_f32 v[204:205], v[204:205], v[210:211]
	v_pk_mul_f32 v[224:225], v[224:225], v[232:233]
	v_pk_mul_f32 v[214:215], v[214:215], v[204:205]
	v_pk_mul_f32 v[242:243], v[242:243], v[224:225]
	s_nop 0
	s_nop 0
	s_nop 0
	s_nop 0
	v_or_b32_e32 v32, s85, v200
	s_ashr_i32 s6, s85, 8
	s_mul_hi_i32 s7, s6, 0x160000
	s_mul_i32 s6, s6, 0x160000
	v_lshlrev_b32_e32 v32, 6, v32
	s_movk_i32 s31, 0x33c0
	v_and_or_b32 v32, v32, s31, v82
	s_add_u32 s40, s86, s6
	s_addc_u32 s41, s87, s7
	v_lshlrev_b32_e32 v164, 1, v32
	v_cvt_pk_bf16_f32 v98, v248, v249
	v_cvt_pk_bf16_f32 v99, v250, v251
	global_store_dwordx4 v164, v[96:99], s[40:41]
	s_and_saveexec_b64 s[6:7], s[36:37]
	s_cbranch_execz .LBB0_1419
	v_mov_b64_e32 v[32:33], s[0:1]
	v_mad_i64_i32 v[32:33], s[36:37], v156, s66, v[32:33]
	v_lshl_add_u64 v[32:33], s[16:17], 1, v[32:33]
	s_lshl_b32 s48, s5, 1
	v_lshl_add_u64 v[32:33], v[32:33], 0, s[48:49]
	v_mov_b32_e32 v179, v165
	v_lshl_add_u64 v[32:33], v[32:33], 0, v[178:179]
	v_cvt_pk_bf16_f32 v34, v28, v29
	v_cvt_pk_bf16_f32 v35, v30, v31
	global_store_dwordx2 v[32:33], v[34:35], off offset:8
	v_cvt_pk_bf16_f32 v34, v24, v25
	v_cvt_pk_bf16_f32 v35, v26, v27
	global_store_dwordx2 v[32:33], v[34:35], off offset:264
.LBB0_1419:
	s_or_b64 exec, exec, s[6:7]
	s_nop 0
	s_nop 0
	s_nop 0
	v_cndmask_b32_e64 v230, v12, v20, vcc
	v_cndmask_b32_e64 v212, v14, v22, vcc
	v_cndmask_b32_e64 v246, v4, v12, vcc
	v_cndmask_b32_e64 v204, v6, v14, vcc
	v_cndmask_b32_e64 v231, v13, v21, vcc
	v_cndmask_b32_e64 v213, v15, v23, vcc
	v_cndmask_b32_e64 v247, v5, v13, vcc
	v_cndmask_b32_e64 v205, v7, v15, vcc
	v_cndmask_b32_e64 v226, v8, v16, vcc
	v_cndmask_b32_e64 v244, v10, v18, vcc
	v_cndmask_b32_e64 v208, v0, v8, vcc
	v_cndmask_b32_e64 v232, v2, v10, vcc
	v_cndmask_b32_e64 v227, v9, v17, vcc
	v_cndmask_b32_e64 v245, v11, v19, vcc
	v_cndmask_b32_e64 v209, v1, v9, vcc
	v_cndmask_b32_e64 v233, v3, v11, vcc
	v_pk_fma_f32 v[206:207], v[12:13], v[68:69], v[84:85]
	v_pk_fma_f32 v[240:241], v[14:15], v[70:71], v[86:87]
	v_pk_fma_f32 v[210:211], v[4:5], v[68:69], v[84:85]
	v_pk_fma_f32 v[234:235], v[6:7], v[70:71], v[86:87]
	v_pk_fma_f32 v[228:229], v[8:9], v[100:101], v[122:123]
	v_pk_fma_f32 v[220:221], v[10:11], v[102:103], v[124:125]
	v_pk_fma_f32 v[222:223], v[0:1], v[100:101], v[122:123]
	v_pk_fma_f32 v[224:225], v[2:3], v[102:103], v[124:125]
	v_fmac_f32_dpp v206, v230, v64 row_ror:1 row_mask:0xf bank_mask:0xf bound_ctrl:1
	v_fmac_f32_dpp v240, v212, v66 row_ror:1 row_mask:0xf bank_mask:0xf bound_ctrl:1
	v_fmac_f32_dpp v210, v246, v64 row_ror:1 row_mask:0xf bank_mask:0xf bound_ctrl:1
	v_fmac_f32_dpp v234, v204, v66 row_ror:1 row_mask:0xf bank_mask:0xf bound_ctrl:1
	v_fmac_f32_dpp v207, v231, v65 row_ror:1 row_mask:0xf bank_mask:0xf bound_ctrl:1
	v_fmac_f32_dpp v241, v213, v67 row_ror:1 row_mask:0xf bank_mask:0xf bound_ctrl:1
	v_fmac_f32_dpp v211, v247, v65 row_ror:1 row_mask:0xf bank_mask:0xf bound_ctrl:1
	v_fmac_f32_dpp v235, v205, v67 row_ror:1 row_mask:0xf bank_mask:0xf bound_ctrl:1
	v_fmac_f32_dpp v228, v226, v92 row_ror:1 row_mask:0xf bank_mask:0xf bound_ctrl:1
	v_fmac_f32_dpp v220, v244, v94 row_ror:1 row_mask:0xf bank_mask:0xf bound_ctrl:1
	v_fmac_f32_dpp v222, v208, v92 row_ror:1 row_mask:0xf bank_mask:0xf bound_ctrl:1
	v_fmac_f32_dpp v224, v232, v94 row_ror:1 row_mask:0xf bank_mask:0xf bound_ctrl:1
	v_fmac_f32_dpp v229, v227, v93 row_ror:1 row_mask:0xf bank_mask:0xf bound_ctrl:1
	v_fmac_f32_dpp v221, v245, v95 row_ror:1 row_mask:0xf bank_mask:0xf bound_ctrl:1
	v_fmac_f32_dpp v223, v209, v93 row_ror:1 row_mask:0xf bank_mask:0xf bound_ctrl:1
	v_fmac_f32_dpp v225, v233, v95 row_ror:1 row_mask:0xf bank_mask:0xf bound_ctrl:1
	v_cndmask_b32_e64 v230, v12, v4, s[34:35]
	v_cndmask_b32_e64 v212, v14, v6, s[34:35]
	v_fmac_f32_dpp v210, v4, v74 row_shl:1 row_mask:0xf bank_mask:0xf bound_ctrl:1
	v_fmac_f32_dpp v234, v6, v76 row_shl:1 row_mask:0xf bank_mask:0xf bound_ctrl:1
	v_cndmask_b32_e64 v231, v13, v5, s[34:35]
	v_cndmask_b32_e64 v213, v15, v7, s[34:35]
	v_fmac_f32_dpp v211, v5, v75 row_shl:1 row_mask:0xf bank_mask:0xf bound_ctrl:1
	v_fmac_f32_dpp v235, v7, v77 row_shl:1 row_mask:0xf bank_mask:0xf bound_ctrl:1
	v_cndmask_b32_e64 v226, v8, v0, s[34:35]
	v_cndmask_b32_e64 v244, v10, v2, s[34:35]
	v_fmac_f32_dpp v222, v0, v108 row_shl:1 row_mask:0xf bank_mask:0xf bound_ctrl:1
	v_fmac_f32_dpp v224, v2, v110 row_shl:1 row_mask:0xf bank_mask:0xf bound_ctrl:1
	v_cndmask_b32_e64 v227, v9, v1, s[34:35]
	v_cndmask_b32_e64 v245, v11, v3, s[34:35]
	v_fmac_f32_dpp v223, v1, v109 row_shl:1 row_mask:0xf bank_mask:0xf bound_ctrl:1
	v_fmac_f32_dpp v225, v3, v111 row_shl:1 row_mask:0xf bank_mask:0xf bound_ctrl:1
	v_fmac_f32_dpp v206, v230, v74 row_ror:15 row_mask:0xf bank_mask:0xf
	v_fmac_f32_dpp v240, v212, v76 row_ror:15 row_mask:0xf bank_mask:0xf
	v_pk_mul_f32 v[246:247], v[254:255], v[210:211]
	v_pk_mul_f32 v[204:205], v[254:255], v[234:235]
	v_fmac_f32_dpp v207, v231, v75 row_ror:15 row_mask:0xf bank_mask:0xf
	v_fmac_f32_dpp v241, v213, v77 row_ror:15 row_mask:0xf bank_mask:0xf
	v_exp_f32_e32 v246, v246
	v_exp_f32_e32 v204, v204
	v_fmac_f32_dpp v228, v226, v108 row_ror:15 row_mask:0xf bank_mask:0xf
	v_fmac_f32_dpp v220, v244, v110 row_ror:15 row_mask:0xf bank_mask:0xf
	v_exp_f32_e32 v247, v247
	v_exp_f32_e32 v205, v205
	v_fmac_f32_dpp v229, v227, v109 row_ror:15 row_mask:0xf bank_mask:0xf
	v_fmac_f32_dpp v221, v245, v111 row_ror:15 row_mask:0xf bank_mask:0xf
	v_pk_add_f32 v[246:247], v[246:247], v[252:253]
	v_pk_add_f32 v[204:205], v[204:205], v[252:253]
	v_pk_mul_f32 v[230:231], v[254:255], v[206:207]
	v_pk_mul_f32 v[212:213], v[254:255], v[240:241]
	v_rcp_f32_e32 v246, v246
	v_rcp_f32_e32 v204, v204
	v_exp_f32_e32 v230, v230
	v_exp_f32_e32 v212, v212
	v_rcp_f32_e32 v247, v247
	v_rcp_f32_e32 v205, v205
	v_exp_f32_e32 v231, v231
	v_exp_f32_e32 v213, v213
	v_pk_mul_f32 v[210:211], v[210:211], v[246:247]
	v_pk_mul_f32 v[234:235], v[234:235], v[204:205]
	v_pk_add_f32 v[230:231], v[230:231], v[252:253]
	v_pk_add_f32 v[212:213], v[212:213], v[252:253]
	v_pk_mul_f32 v[222:223], v[222:223], v[210:211]
	v_pk_mul_f32 v[224:225], v[224:225], v[234:235]
	v_rcp_f32_e32 v230, v230
	v_rcp_f32_e32 v212, v212
	v_rcp_f32_e32 v231, v231
	v_rcp_f32_e32 v213, v213
	v_pk_mul_f32 v[206:207], v[206:207], v[230:231]
	v_pk_mul_f32 v[240:241], v[240:241], v[212:213]
	v_pk_mul_f32 v[228:229], v[228:229], v[206:207]
	v_pk_mul_f32 v[220:221], v[220:221], v[240:241]
	s_nop 0
	v_cvt_pk_bf16_f32 v90, v214, v215
	s_nop 0
	v_cvt_pk_bf16_f32 v91, v242, v243
	s_nop 0
	s_nop 0
	s_nop 0
	v_cvt_pk_bf16_f32 v83, v220, v221
	s_nop 0
	s_nop 0
	s_nop 0
	v_lshl_add_u64 v[32:33], s[40:41], 0, v[164:165]
	s_movk_i32 s6, 0x1000
	v_cvt_pk_bf16_f32 v82, v228, v229
	v_add_co_u32_e64 v16, s[36:37], s6, v32
	s_nop 0
	s_nop 0
	v_addc_co_u32_e64 v17, s[36:37], 0, v33, s[36:37]
	global_store_dwordx4 v[32:33], v[88:91], off offset:2048
	global_store_dwordx4 v[16:17], v[80:83], off
	v_cvt_pk_bf16_f32 v74, v222, v223
	v_cvt_pk_bf16_f32 v75, v224, v225
	global_store_dwordx4 v[16:17], v[72:75], off offset:2048
	s_and_saveexec_b64 s[34:35], s[38:39]
	s_cbranch_execz .LBB0_1392
	v_mov_b32_e32 v181, v165
	v_lshl_add_u64 v[8:9], s[10:11], 0, v[180:181]
	v_mov_b64_e32 v[10:11], s[0:1]
	s_movk_i32 s10, 0x2c00
	v_mad_u64_u32 v[10:11], s[6:7], v8, s10, v[10:11]
	v_mad_i32_i24 v11, v9, s10, v11
	v_lshl_add_u64 v[8:9], s[16:17], 1, v[10:11]
	s_lshl_b32 s48, s5, 1
	v_lshl_add_u64 v[8:9], v[8:9], 0, s[48:49]
	v_mov_b32_e32 v179, v165
	s_movk_i32 s66, 0x2c00
	v_lshl_add_u64 v[8:9], v[8:9], 0, v[178:179]
	v_cvt_pk_bf16_f32 v4, v4, v5
	v_cvt_pk_bf16_f32 v5, v6, v7
	global_store_dwordx2 v[8:9], v[4:5], off offset:8
	v_cvt_pk_bf16_f32 v0, v0, v1
	v_cvt_pk_bf16_f32 v1, v2, v3
	global_store_dwordx2 v[8:9], v[0:1], off offset:264
	s_branch .LBB0_1392
